# speedup vs baseline: 1.0028x; 1.0028x over previous
; DI float bf2f(short b) { return __uint_as_float(((unsigned)(unsigned short)b) << 16); }
; DI bf16x8 pack8(const float* a) { u32x4 w = {cvtpk(a[0], a[1]), cvtpk(a[2], a[3]), cvtpk(a[4], a[5]), cvtpk(a[6], a[7])}; return *reinterpret_cast<bf16x8*>(&w); }
; DI float sigm(float x) { return __builtin_amdgcn_rcpf(1.f + __builtin_amdgcn_exp2f(-1.4426950408889634f * x)); }
; DI void gemm8_run(const GemmJob& ja, const GemmJob& jb, char* lds) {
;     ...
;           for (int it = 0; it < 4; ++it) { const int idx = (hb * 4 + it) * 512 + tid; const int r = idx >> 5, c16 = idx & 31; const size_t grow = (size_t)(brow + ai * 128 + r);
;             av[it] = *reinterpret_cast<const bf16x8*>(lds + r * 528 + c16 * 16);
;             gv[it] = ld8(J.gsrc + grow * INP + bcol + c16 * 8);
;             if (gb) ov[it] = ld8(J.C + grow * 1024 + bcol + c16 * 8); else ov[it] = av[it]; }
; #pragma unroll
;           for (int it = 0; it < 4; ++it) { const int idx = (hb * 4 + it) * 512 + tid; const int r = idx >> 5, c16 = idx & 31; const size_t grow = (size_t)(brow + ai * 128 + r);
;             const float4 b0 = *reinterpret_cast<const float4*>(J.bias + bcol + c16 * 8), b1 = *reinterpret_cast<const float4*>(J.bias + bcol + c16 * 8 + 4);
;             const float bb[8] = {b0.x, b0.y, b0.z, b0.w, b1.x, b1.y, b1.z, b1.w};
;             float o8[8];
; #pragma unroll
;             for (int j = 0; j < 8; ++j) { const float g = sigm(bf2f(gv[it][j]) + bb[j]); o8[j] = (gb ? bf2f(ov[it][j]) : 0.f) + bf2f(av[it][j]) * g; }
;             *reinterpret_cast<bf16x8*>(J.C + grow * 1024 + bcol + c16 * 8) = pack8(o8); } }
.LBB0_229:
	s_lshl_b64 s[78:79], s[12:13], 2
	v_lshlrev_b32_e32 v96, 3, v179
	s_add_u32 s78, s48, s78
	v_and_b32_e32 v96, 0xf8, v96
	s_addc_u32 s79, s49, s79
	v_lshlrev_b32_e32 v178, 2, v96
	global_load_dwordx4 v[248:251], v178, s[78:79]
	global_load_dwordx4 v[238:241], v178, s[78:79] offset:16
	s_waitcnt vmcnt(5)
	v_lshlrev_b32_e32 v182, 16, v174
	v_lshlrev_b32_e32 v183, 16, v175
	v_lshlrev_b32_e32 v96, 1, v96
	v_lshlrev_b32_e32 v203, 16, v170
	v_and_b32_e32 v214, 0xffff0000, v170
	v_and_b32_e32 v170, 0xffff0000, v174
	v_lshlrev_b32_e32 v174, 16, v171
	v_and_b32_e32 v216, 0xffff0000, v171
	v_and_b32_e32 v171, 0xffff0000, v175
	v_lshlrev_b32_e32 v175, 16, v172
	v_and_b32_e32 v172, 0xffff0000, v172
	v_lshlrev_b32_e32 v219, 16, v173
	v_and_b32_e32 v173, 0xffff0000, v173
	v_cndmask_b32_e64 v222, 0, v182, s[40:41]
	v_cndmask_b32_e64 v224, 0, v183, s[40:41]
	v_lshl_add_u64 v[182:183], s[80:81], 0, v[96:97]
	v_cndmask_b32_e64 v223, 0, v170, s[40:41]
	v_cndmask_b32_e64 v225, 0, v171, s[40:41]
	v_lshl_add_u64 v[170:171], v[182:183], 0, v[192:193]
	v_lshlrev_b32_e32 v217, 16, v176
	v_and_b32_e32 v176, 0xffff0000, v176
	v_lshlrev_b32_e32 v220, 16, v177
	v_and_b32_e32 v177, 0xffff0000, v177
	v_lshlrev_b32_e32 v204, 16, v166
	v_and_b32_e32 v166, 0xffff0000, v166
	v_lshlrev_b32_e32 v215, 16, v167
	v_and_b32_e32 v167, 0xffff0000, v167
	v_lshlrev_b32_e32 v218, 16, v168
	v_and_b32_e32 v168, 0xffff0000, v168
	v_lshlrev_b32_e32 v221, 16, v169
	v_and_b32_e32 v169, 0xffff0000, v169
	v_cndmask_b32_e64 v217, 0, v217, s[40:41]
	v_cndmask_b32_e64 v176, 0, v176, s[40:41]
	v_cndmask_b32_e64 v220, 0, v220, s[40:41]
	v_cndmask_b32_e64 v177, 0, v177, s[40:41]
	s_and_b64 vcc, exec, s[42:43]
	s_waitcnt vmcnt(1)
	v_add_f32_e32 v96, v248, v203
	v_add_f32_e32 v192, v249, v214
	v_add_f32_e32 v174, v250, v174
	v_add_f32_e32 v193, v251, v216
	s_waitcnt vmcnt(0)
	v_add_f32_e32 v175, v238, v175
	v_add_f32_e32 v172, v239, v172
	v_add_f32_e32 v194, v240, v219
	v_add_f32_e32 v173, v241, v173
	v_mul_f32_e32 v96, 0xbfb8aa3b, v96
	v_mul_f32_e32 v192, 0xbfb8aa3b, v192
	v_mul_f32_e32 v174, 0xbfb8aa3b, v174
	v_mul_f32_e32 v193, 0xbfb8aa3b, v193
	v_mul_f32_e32 v175, 0xbfb8aa3b, v175
	v_mul_f32_e32 v172, 0xbfb8aa3b, v172
	v_mul_f32_e32 v194, 0xbfb8aa3b, v194
	v_mul_f32_e32 v173, 0xbfb8aa3b, v173
	v_exp_f32_e32 v96, v96
	v_exp_f32_e32 v192, v192
	v_exp_f32_e32 v174, v174
	v_exp_f32_e32 v193, v193
	v_exp_f32_e32 v175, v175
	v_exp_f32_e32 v172, v172
	v_exp_f32_e32 v194, v194
	v_exp_f32_e32 v173, v173
	v_add_f32_e32 v96, 1.0, v96
	v_add_f32_e32 v192, 1.0, v192
	v_add_f32_e32 v174, 1.0, v174
	v_add_f32_e32 v193, 1.0, v193
	v_add_f32_e32 v175, 1.0, v175
	v_add_f32_e32 v172, 1.0, v172
	v_add_f32_e32 v194, 1.0, v194
	v_add_f32_e32 v173, 1.0, v173
	v_rcp_f32_e32 v96, v96
	v_rcp_f32_e32 v192, v192
	v_rcp_f32_e32 v174, v174
	v_rcp_f32_e32 v193, v193
	v_rcp_f32_e32 v175, v175
	v_rcp_f32_e32 v172, v172
	v_rcp_f32_e32 v194, v194
	v_rcp_f32_e32 v173, v173
	v_fmac_f32_e32 v222, v96, v204
	v_fmac_f32_e32 v223, v192, v166
	v_fmac_f32_e32 v224, v174, v215
	v_fmac_f32_e32 v225, v193, v167
	v_fmac_f32_e32 v217, v175, v218
	v_fmac_f32_e32 v176, v172, v168
	v_fmac_f32_e32 v220, v194, v221
	v_fmac_f32_e32 v177, v173, v169
	v_cvt_pk_bf16_f32 v166, v222, v223
	v_cvt_pk_bf16_f32 v167, v224, v225
	v_cvt_pk_bf16_f32 v168, v217, v176
	v_cvt_pk_bf16_f32 v169, v220, v177
	global_store_dwordx4 v[170:171], v[166:169], off
	s_nop 0
	v_lshlrev_b32_e32 v96, 16, v158
	v_lshlrev_b32_e32 v174, 16, v162
	v_and_b32_e32 v176, 0xffff0000, v158
	v_and_b32_e32 v158, 0xffff0000, v162
	v_lshlrev_b32_e32 v162, 16, v159
	v_lshlrev_b32_e32 v177, 16, v163
	v_and_b32_e32 v193, 0xffff0000, v159
	v_and_b32_e32 v159, 0xffff0000, v163
	v_lshlrev_b32_e32 v163, 16, v160
	v_and_b32_e32 v160, 0xffff0000, v160
	v_lshlrev_b32_e32 v196, 16, v161
	v_and_b32_e32 v161, 0xffff0000, v161
	v_lshlrev_b32_e32 v194, 16, v164
	v_and_b32_e32 v164, 0xffff0000, v164
	v_lshlrev_b32_e32 v197, 16, v165
	v_and_b32_e32 v165, 0xffff0000, v165
	v_lshlrev_b32_e32 v175, 16, v154
	v_and_b32_e32 v154, 0xffff0000, v154
	v_lshlrev_b32_e32 v192, 16, v155
	v_and_b32_e32 v155, 0xffff0000, v155
	v_lshlrev_b32_e32 v195, 16, v156
	v_and_b32_e32 v156, 0xffff0000, v156
	v_lshlrev_b32_e32 v198, 16, v157
	v_and_b32_e32 v157, 0xffff0000, v157
	v_cndmask_b32_e64 v174, 0, v174, s[40:41]
	v_cndmask_b32_e64 v199, 0, v158, s[40:41]
	v_cndmask_b32_e64 v177, 0, v177, s[40:41]
	v_cndmask_b32_e64 v200, 0, v159, s[40:41]
	v_cndmask_b32_e64 v194, 0, v194, s[40:41]
	v_cndmask_b32_e64 v164, 0, v164, s[40:41]
	v_cndmask_b32_e64 v197, 0, v197, s[40:41]
	v_cndmask_b32_e64 v165, 0, v165, s[40:41]
	v_lshl_add_u64 v[158:159], v[182:183], 0, v[190:191]
	v_add_f32_e32 v96, v248, v96
	v_add_f32_e32 v166, v249, v176
	v_add_f32_e32 v162, v250, v162
	v_add_f32_e32 v167, v251, v193
	v_add_f32_e32 v163, v238, v163
	v_add_f32_e32 v160, v239, v160
	v_add_f32_e32 v168, v240, v196
	v_add_f32_e32 v161, v241, v161
	v_mul_f32_e32 v96, 0xbfb8aa3b, v96
	v_mul_f32_e32 v166, 0xbfb8aa3b, v166
	v_mul_f32_e32 v162, 0xbfb8aa3b, v162
	v_mul_f32_e32 v167, 0xbfb8aa3b, v167
	v_mul_f32_e32 v163, 0xbfb8aa3b, v163
	v_mul_f32_e32 v160, 0xbfb8aa3b, v160
	v_mul_f32_e32 v168, 0xbfb8aa3b, v168
	v_mul_f32_e32 v161, 0xbfb8aa3b, v161
	v_exp_f32_e32 v96, v96
	v_exp_f32_e32 v166, v166
	v_exp_f32_e32 v162, v162
	v_exp_f32_e32 v167, v167
	v_exp_f32_e32 v163, v163
	v_exp_f32_e32 v160, v160
	v_exp_f32_e32 v168, v168
	v_exp_f32_e32 v161, v161
	v_add_f32_e32 v96, 1.0, v96
	v_add_f32_e32 v166, 1.0, v166
	v_add_f32_e32 v162, 1.0, v162
	v_add_f32_e32 v167, 1.0, v167
	v_add_f32_e32 v163, 1.0, v163
	v_add_f32_e32 v160, 1.0, v160
	v_add_f32_e32 v168, 1.0, v168
; DI float bf2f(short b) { return __uint_as_float(((unsigned)(unsigned short)b) << 16); }
; DI bf16x8 pack8(const float* a) { u32x4 w = {cvtpk(a[0], a[1]), cvtpk(a[2], a[3]), cvtpk(a[4], a[5]), cvtpk(a[6], a[7])}; return *reinterpret_cast<bf16x8*>(&w); }
; DI float sigm(float x) { return __builtin_amdgcn_rcpf(1.f + __builtin_amdgcn_exp2f(-1.4426950408889634f * x)); }
; DI void gemm8_run(const GemmJob& ja, const GemmJob& jb, char* lds) {
;     ...
;           for (int it = 0; it < 4; ++it) { const int idx = (hb * 4 + it) * 512 + tid; const int r = idx >> 5, c16 = idx & 31; const size_t grow = (size_t)(brow + ai * 128 + r);
;             av[it] = *reinterpret_cast<const bf16x8*>(lds + r * 528 + c16 * 16);
;             gv[it] = ld8(J.gsrc + grow * INP + bcol + c16 * 8);
;             if (gb) ov[it] = ld8(J.C + grow * 1024 + bcol + c16 * 8); else ov[it] = av[it]; }
; #pragma unroll
;           for (int it = 0; it < 4; ++it) { const int idx = (hb * 4 + it) * 512 + tid; const int r = idx >> 5, c16 = idx & 31; const size_t grow = (size_t)(brow + ai * 128 + r);
;             const float4 b0 = *reinterpret_cast<const float4*>(J.bias + bcol + c16 * 8), b1 = *reinterpret_cast<const float4*>(J.bias + bcol + c16 * 8 + 4);
;             const float bb[8] = {b0.x, b0.y, b0.z, b0.w, b1.x, b1.y, b1.z, b1.w};
;             float o8[8];
; #pragma unroll
;             for (int j = 0; j < 8; ++j) { const float g = sigm(bf2f(gv[it][j]) + bb[j]); o8[j] = (gb ? bf2f(ov[it][j]) : 0.f) + bf2f(av[it][j]) * g; }
;             *reinterpret_cast<bf16x8*>(J.C + grow * 1024 + bcol + c16 * 8) = pack8(o8); } }
	v_add_f32_e32 v161, 1.0, v161
	v_rcp_f32_e32 v96, v96
	v_rcp_f32_e32 v166, v166
	v_rcp_f32_e32 v162, v162
	v_rcp_f32_e32 v167, v167
	v_rcp_f32_e32 v163, v163
	v_rcp_f32_e32 v160, v160
	v_rcp_f32_e32 v168, v168
	v_rcp_f32_e32 v161, v161
	v_fmac_f32_e32 v174, v96, v175
	v_fmac_f32_e32 v199, v166, v154
	v_fmac_f32_e32 v177, v162, v192
	v_fmac_f32_e32 v200, v167, v155
	v_fmac_f32_e32 v194, v163, v195
	v_fmac_f32_e32 v164, v160, v156
	v_fmac_f32_e32 v197, v168, v198
	v_fmac_f32_e32 v165, v161, v157
	v_cvt_pk_bf16_f32 v154, v174, v199
	v_cvt_pk_bf16_f32 v155, v177, v200
	v_cvt_pk_bf16_f32 v156, v194, v164
	v_cvt_pk_bf16_f32 v157, v197, v165
	global_store_dwordx4 v[158:159], v[154:157], off
	s_nop 0
	v_lshlrev_b32_e32 v96, 16, v146
	v_lshlrev_b32_e32 v162, 16, v150
	v_and_b32_e32 v164, 0xffff0000, v146
	v_and_b32_e32 v146, 0xffff0000, v150
	v_lshlrev_b32_e32 v150, 16, v147
	v_lshlrev_b32_e32 v165, 16, v151
	v_and_b32_e32 v167, 0xffff0000, v147
	v_and_b32_e32 v147, 0xffff0000, v151
	v_lshlrev_b32_e32 v151, 16, v148
	v_and_b32_e32 v148, 0xffff0000, v148
	v_lshlrev_b32_e32 v170, 16, v149
	v_and_b32_e32 v149, 0xffff0000, v149
	v_lshlrev_b32_e32 v168, 16, v152
	v_and_b32_e32 v152, 0xffff0000, v152
	v_lshlrev_b32_e32 v171, 16, v153
	v_and_b32_e32 v153, 0xffff0000, v153
	v_lshlrev_b32_e32 v163, 16, v142
	v_and_b32_e32 v142, 0xffff0000, v142
	v_lshlrev_b32_e32 v166, 16, v143
	v_and_b32_e32 v143, 0xffff0000, v143
	v_lshlrev_b32_e32 v169, 16, v144
	v_and_b32_e32 v144, 0xffff0000, v144
	v_lshlrev_b32_e32 v172, 16, v145
	v_and_b32_e32 v145, 0xffff0000, v145
	v_cndmask_b32_e64 v162, 0, v162, s[40:41]
	v_cndmask_b32_e64 v173, 0, v146, s[40:41]
	v_cndmask_b32_e64 v165, 0, v165, s[40:41]
	v_cndmask_b32_e64 v174, 0, v147, s[40:41]
	v_cndmask_b32_e64 v168, 0, v168, s[40:41]
	v_cndmask_b32_e64 v152, 0, v152, s[40:41]
	v_cndmask_b32_e64 v171, 0, v171, s[40:41]
	v_cndmask_b32_e64 v153, 0, v153, s[40:41]
	v_lshl_add_u64 v[146:147], v[182:183], 0, v[184:185]
	v_add_f32_e32 v96, v248, v96
	v_add_f32_e32 v154, v249, v164
	v_add_f32_e32 v150, v250, v150
	v_add_f32_e32 v155, v251, v167
	v_add_f32_e32 v151, v238, v151
	v_add_f32_e32 v148, v239, v148
	v_add_f32_e32 v156, v240, v170
	v_add_f32_e32 v149, v241, v149
	v_mul_f32_e32 v96, 0xbfb8aa3b, v96
	v_mul_f32_e32 v154, 0xbfb8aa3b, v154
	v_mul_f32_e32 v150, 0xbfb8aa3b, v150
	v_mul_f32_e32 v155, 0xbfb8aa3b, v155
	v_mul_f32_e32 v151, 0xbfb8aa3b, v151
	v_mul_f32_e32 v148, 0xbfb8aa3b, v148
	v_mul_f32_e32 v156, 0xbfb8aa3b, v156
	v_mul_f32_e32 v149, 0xbfb8aa3b, v149
	v_exp_f32_e32 v96, v96
	v_exp_f32_e32 v154, v154
	v_exp_f32_e32 v150, v150
	v_exp_f32_e32 v155, v155
	v_exp_f32_e32 v151, v151
	v_exp_f32_e32 v148, v148
	v_exp_f32_e32 v156, v156
	v_exp_f32_e32 v149, v149
	v_add_f32_e32 v96, 1.0, v96
	v_add_f32_e32 v154, 1.0, v154
	v_add_f32_e32 v150, 1.0, v150
	v_add_f32_e32 v155, 1.0, v155
	v_add_f32_e32 v151, 1.0, v151
	v_add_f32_e32 v148, 1.0, v148
	v_add_f32_e32 v156, 1.0, v156
	v_add_f32_e32 v149, 1.0, v149
	v_rcp_f32_e32 v96, v96
	v_rcp_f32_e32 v154, v154
	v_rcp_f32_e32 v150, v150
	v_rcp_f32_e32 v155, v155
	v_rcp_f32_e32 v151, v151
	v_rcp_f32_e32 v148, v148
	v_rcp_f32_e32 v156, v156
	v_rcp_f32_e32 v149, v149
	v_fmac_f32_e32 v162, v96, v163
	v_fmac_f32_e32 v173, v154, v142
	v_fmac_f32_e32 v165, v150, v166
	v_fmac_f32_e32 v174, v155, v143
	v_fmac_f32_e32 v168, v151, v169
	v_fmac_f32_e32 v152, v148, v144
	v_fmac_f32_e32 v171, v156, v172
	v_fmac_f32_e32 v153, v149, v145
	v_cvt_pk_bf16_f32 v142, v162, v173
	v_cvt_pk_bf16_f32 v143, v165, v174
	v_cvt_pk_bf16_f32 v144, v168, v152
	v_cvt_pk_bf16_f32 v145, v171, v153
	global_store_dwordx4 v[146:147], v[142:145], off
	s_nop 0
	v_lshlrev_b32_e32 v96, 16, v134
	v_lshlrev_b32_e32 v150, 16, v138
	v_and_b32_e32 v152, 0xffff0000, v134
	v_and_b32_e32 v134, 0xffff0000, v138
	v_lshlrev_b32_e32 v138, 16, v135
	v_and_b32_e32 v135, 0xffff0000, v135
	v_lshlrev_b32_e32 v155, 16, v136
	v_lshlrev_b32_e32 v156, 16, v140
	v_and_b32_e32 v158, 0xffff0000, v136
	v_and_b32_e32 v136, 0xffff0000, v140
	v_lshlrev_b32_e32 v140, 16, v137
	v_lshlrev_b32_e32 v159, 16, v141
	v_and_b32_e32 v161, 0xffff0000, v137
	v_and_b32_e32 v137, 0xffff0000, v141
	v_add_u32_e32 v141, 0x800, v179
	v_ashrrev_i32_e32 v203, 5, v141
	v_lshlrev_b32_e32 v153, 16, v139
	v_and_b32_e32 v139, 0xffff0000, v139
	v_lshlrev_b32_e32 v151, 16, v130
	v_and_b32_e32 v130, 0xffff0000, v130
	v_lshlrev_b32_e32 v154, 16, v131
	v_and_b32_e32 v131, 0xffff0000, v131
	v_cndmask_b32_e64 v150, 0, v150, s[40:41]
	v_cndmask_b32_e64 v162, 0, v134, s[40:41]
	v_cndmask_b32_e64 v153, 0, v153, s[40:41]
	v_cndmask_b32_e64 v139, 0, v139, s[40:41]
	v_lshlrev_b32_e32 v157, 16, v132
	v_and_b32_e32 v132, 0xffff0000, v132
	v_lshlrev_b32_e32 v160, 16, v133
	v_and_b32_e32 v133, 0xffff0000, v133
	v_cndmask_b32_e64 v156, 0, v156, s[40:41]
	v_cndmask_b32_e64 v163, 0, v136, s[40:41]
	v_cndmask_b32_e64 v159, 0, v159, s[40:41]
	v_cndmask_b32_e64 v164, 0, v137, s[40:41]
	v_add_u32_e32 v134, s96, v203
	v_lshl_add_u64 v[136:137], v[182:183], 0, v[180:181]
	v_add_f32_e32 v96, v248, v96
	v_add_f32_e32 v141, v249, v152
	v_add_f32_e32 v138, v250, v138
	v_add_f32_e32 v135, v251, v135
	v_add_f32_e32 v142, v238, v155
	v_add_f32_e32 v143, v239, v158
	v_add_f32_e32 v140, v240, v140
	v_add_f32_e32 v144, v241, v161
	v_mul_f32_e32 v96, 0xbfb8aa3b, v96
	v_mul_f32_e32 v141, 0xbfb8aa3b, v141
	v_mul_f32_e32 v138, 0xbfb8aa3b, v138
	v_mul_f32_e32 v135, 0xbfb8aa3b, v135
	v_mul_f32_e32 v142, 0xbfb8aa3b, v142
	v_mul_f32_e32 v143, 0xbfb8aa3b, v143
	v_mul_f32_e32 v140, 0xbfb8aa3b, v140
	v_mul_f32_e32 v144, 0xbfb8aa3b, v144
	v_exp_f32_e32 v96, v96
	v_exp_f32_e32 v141, v141
	v_exp_f32_e32 v138, v138
	v_exp_f32_e32 v135, v135
	v_exp_f32_e32 v142, v142
	v_exp_f32_e32 v143, v143
	v_exp_f32_e32 v140, v140
	v_exp_f32_e32 v144, v144
	v_add_f32_e32 v96, 1.0, v96
	v_add_f32_e32 v141, 1.0, v141
	v_add_f32_e32 v138, 1.0, v138
	v_add_f32_e32 v135, 1.0, v135
	v_add_f32_e32 v142, 1.0, v142
	v_add_f32_e32 v143, 1.0, v143
	v_add_f32_e32 v140, 1.0, v140
	v_add_f32_e32 v144, 1.0, v144
	v_rcp_f32_e32 v96, v96
	v_rcp_f32_e32 v141, v141
	v_rcp_f32_e32 v138, v138
	v_rcp_f32_e32 v135, v135
	v_rcp_f32_e32 v142, v142
	v_rcp_f32_e32 v143, v143
	v_rcp_f32_e32 v140, v140
	v_rcp_f32_e32 v144, v144
	v_fmac_f32_e32 v150, v96, v151
	v_fmac_f32_e32 v162, v141, v130
	v_fmac_f32_e32 v153, v138, v154
	v_fmac_f32_e32 v139, v135, v131
	v_cvt_pk_bf16_f32 v130, v150, v162
	v_cvt_pk_bf16_f32 v131, v153, v139
	v_fmac_f32_e32 v156, v142, v157
	v_fmac_f32_e32 v163, v143, v132
	v_fmac_f32_e32 v159, v140, v160
	v_fmac_f32_e32 v164, v144, v133
	v_cvt_pk_bf16_f32 v132, v156, v163
	v_cvt_pk_bf16_f32 v133, v159, v164
	global_store_dwordx4 v[136:137], v[130:133], off
	v_mul_lo_u32 v96, v203, s11
	v_add_u32_e32 v204, v202, v96
	v_mad_i64_i32 v[130:131], s[80:81], v134, s33, v[186:187]
	global_load_dwordx4 v[174:177], v[130:131], off
	ds_read_b128 v[166:169], v204
	v_ashrrev_i32_e32 v135, 31, v134
	v_lshlrev_b64 v[196:197], 11, v[134:135]
	s_waitcnt lgkmcnt(0)
; DI void gemm8_run(const GemmJob& ja, const GemmJob& jb, char* lds) {
;     ...
;           for (int it = 0; it < 4; ++it) { const int idx = (hb * 4 + it) * 512 + tid; const int r = idx >> 5, c16 = idx & 31; const size_t grow = (size_t)(brow + ai * 128 + r);
;             av[it] = *reinterpret_cast<const bf16x8*>(lds + r * 528 + c16 * 16);
;             gv[it] = ld8(J.gsrc + grow * INP + bcol + c16 * 8);
;             if (gb) ov[it] = ld8(J.C + grow * 1024 + bcol + c16 * 8); else ov[it] = av[it]; }
	v_mov_b64_e32 v[172:173], v[168:169]
	v_mov_b64_e32 v[170:171], v[166:167]
	s_cbranch_vccnz .LBB0_231
	v_lshl_add_u64 v[130:131], v[188:189], 0, v[196:197]
	global_load_dwordx4 v[170:173], v[130:131], off

; DI float bf2f(short b) { return __uint_as_float(((unsigned)(unsigned short)b) << 16); }
; DI bf16x8 pack8(const float* a) { u32x4 w = {cvtpk(a[0], a[1]), cvtpk(a[2], a[3]), cvtpk(a[4], a[5]), cvtpk(a[6], a[7])}; return *reinterpret_cast<bf16x8*>(&w); }
; DI float sigm(float x) { return __builtin_amdgcn_rcpf(1.f + __builtin_amdgcn_exp2f(-1.4426950408889634f * x)); }
; DI void gemm8_run(const GemmJob& ja, const GemmJob& jb, char* lds) {
;     ...
;           for (int it = 0; it < 4; ++it) { const int idx = (hb * 4 + it) * 512 + tid; const int r = idx >> 5, c16 = idx & 31; const size_t grow = (size_t)(brow + ai * 128 + r);
;             const float4 b0 = *reinterpret_cast<const float4*>(J.bias + bcol + c16 * 8), b1 = *reinterpret_cast<const float4*>(J.bias + bcol + c16 * 8 + 4);
;             const float bb[8] = {b0.x, b0.y, b0.z, b0.w, b1.x, b1.y, b1.z, b1.w};
;             float o8[8];
; #pragma unroll
;             for (int j = 0; j < 8; ++j) { const float g = sigm(bf2f(gv[it][j]) + bb[j]); o8[j] = (gb ? bf2f(ov[it][j]) : 0.f) + bf2f(av[it][j]) * g; }
;             *reinterpret_cast<bf16x8*>(J.C + grow * 1024 + bcol + c16 * 8) = pack8(o8); } }
.LBB0_237:
	v_mov_b32_e32 v179, v97
	v_lshl_add_u64 v[184:185], s[78:79], 0, v[178:179]
	s_waitcnt vmcnt(3)
	v_lshlrev_b32_e32 v218, 16, v174
	v_and_b32_e32 v174, 0xffff0000, v174
	v_lshlrev_b32_e32 v219, 16, v166
	v_and_b32_e32 v166, 0xffff0000, v166
	s_and_b64 vcc, exec, s[42:43]
	s_waitcnt vmcnt(0)
	v_add_f32_e32 v174, v249, v174
	v_mul_f32_e32 v174, 0xbfb8aa3b, v174
	v_exp_f32_e32 v174, v174
	v_add_f32_e32 v214, v248, v218
	v_lshlrev_b32_e32 v218, 16, v170
	v_and_b32_e32 v170, 0xffff0000, v170
	v_add_f32_e32 v174, 1.0, v174
	v_rcp_f32_e32 v174, v174
	v_cndmask_b32_e64 v170, 0, v170, s[40:41]
	v_mul_f32_e32 v214, 0xbfb8aa3b, v214
	v_exp_f32_e32 v214, v214
	v_fmac_f32_e32 v170, v174, v166
	v_lshlrev_b32_e32 v166, 16, v175
	v_add_f32_e32 v166, v250, v166
	v_mul_f32_e32 v166, 0xbfb8aa3b, v166
	v_exp_f32_e32 v166, v166
	v_add_f32_e32 v214, 1.0, v214
	v_rcp_f32_e32 v214, v214
	v_cndmask_b32_e64 v218, 0, v218, s[40:41]
	v_add_f32_e32 v166, 1.0, v166
	v_rcp_f32_e32 v166, v166
	v_lshlrev_b32_e32 v174, 16, v171
	v_fmac_f32_e32 v218, v214, v219
	v_cndmask_b32_e64 v174, 0, v174, s[40:41]
	v_lshlrev_b32_e32 v214, 16, v167
	v_fmac_f32_e32 v174, v166, v214
	v_and_b32_e32 v166, 0xffff0000, v175
	v_add_f32_e32 v166, v251, v166
	v_mul_f32_e32 v166, 0xbfb8aa3b, v166
	v_exp_f32_e32 v166, v166
	v_and_b32_e32 v171, 0xffff0000, v171
	v_cndmask_b32_e64 v171, 0, v171, s[40:41]
	v_and_b32_e32 v167, 0xffff0000, v167
	v_add_f32_e32 v166, 1.0, v166
	v_rcp_f32_e32 v166, v166
	s_nop 0
	v_fmac_f32_e32 v171, v166, v167
	v_lshlrev_b32_e32 v166, 16, v176
	v_add_f32_e32 v166, v238, v166
	v_mul_f32_e32 v166, 0xbfb8aa3b, v166
	v_exp_f32_e32 v166, v166
	v_lshlrev_b32_e32 v167, 16, v172
	v_cndmask_b32_e64 v175, 0, v167, s[40:41]
	v_lshlrev_b32_e32 v167, 16, v168
	v_add_f32_e32 v166, 1.0, v166
	v_rcp_f32_e32 v166, v166
	s_nop 0
	v_fmac_f32_e32 v175, v166, v167
	v_and_b32_e32 v166, 0xffff0000, v176
	v_add_f32_e32 v166, v239, v166
	v_mul_f32_e32 v166, 0xbfb8aa3b, v166
	v_exp_f32_e32 v166, v166
	v_and_b32_e32 v167, 0xffff0000, v172
	v_cndmask_b32_e64 v172, 0, v167, s[40:41]
	v_and_b32_e32 v167, 0xffff0000, v168
	v_add_f32_e32 v166, 1.0, v166
	v_rcp_f32_e32 v166, v166
	s_nop 0
	v_fmac_f32_e32 v172, v166, v167
	v_lshlrev_b32_e32 v166, 16, v177
	v_add_f32_e32 v166, v240, v166
	v_mul_f32_e32 v166, 0xbfb8aa3b, v166
	v_exp_f32_e32 v166, v166
	v_lshlrev_b32_e32 v167, 16, v173
	v_cndmask_b32_e64 v176, 0, v167, s[40:41]
	v_lshlrev_b32_e32 v167, 16, v169
	v_add_f32_e32 v166, 1.0, v166
	v_rcp_f32_e32 v166, v166
	s_nop 0
	v_fmac_f32_e32 v176, v166, v167
	v_and_b32_e32 v166, 0xffff0000, v177
	v_add_f32_e32 v166, v241, v166
	v_mul_f32_e32 v166, 0xbfb8aa3b, v166
	v_exp_f32_e32 v166, v166
	v_and_b32_e32 v167, 0xffff0000, v173
	v_cndmask_b32_e64 v173, 0, v167, s[40:41]
	v_and_b32_e32 v167, 0xffff0000, v169
	v_add_f32_e32 v166, 1.0, v166
	v_rcp_f32_e32 v166, v166
	s_nop 0
	v_fmac_f32_e32 v173, v166, v167
	v_cvt_pk_bf16_f32 v166, v218, v170
	v_cvt_pk_bf16_f32 v167, v174, v171
	v_lshl_add_u64 v[170:171], v[182:183], 0, v[196:197]
	v_cvt_pk_bf16_f32 v168, v175, v172
	v_cvt_pk_bf16_f32 v169, v176, v173
	global_store_dwordx4 v[170:171], v[166:169], off
	s_nop 0
	v_lshlrev_b32_e32 v174, 16, v162
	v_and_b32_e32 v162, 0xffff0000, v162
	v_lshlrev_b32_e32 v175, 16, v154
	v_and_b32_e32 v154, 0xffff0000, v154
	v_add_f32_e32 v162, v249, v162
	v_mul_f32_e32 v162, 0xbfb8aa3b, v162
	v_exp_f32_e32 v162, v162
	v_add_f32_e32 v170, v248, v174
	v_lshlrev_b32_e32 v174, 16, v158
	v_and_b32_e32 v158, 0xffff0000, v158
	v_add_f32_e32 v162, 1.0, v162
	v_rcp_f32_e32 v162, v162
	v_cndmask_b32_e64 v158, 0, v158, s[40:41]
	v_mul_f32_e32 v170, 0xbfb8aa3b, v170
	v_exp_f32_e32 v170, v170
	v_fmac_f32_e32 v158, v162, v154
	v_lshlrev_b32_e32 v154, 16, v163
	v_add_f32_e32 v154, v250, v154
	v_mul_f32_e32 v154, 0xbfb8aa3b, v154
	v_exp_f32_e32 v154, v154
	v_add_f32_e32 v170, 1.0, v170
	v_rcp_f32_e32 v170, v170
	v_cndmask_b32_e64 v174, 0, v174, s[40:41]
	v_add_f32_e32 v154, 1.0, v154
	v_rcp_f32_e32 v154, v154
	v_lshlrev_b32_e32 v162, 16, v159
	v_fmac_f32_e32 v174, v170, v175
	v_cndmask_b32_e64 v162, 0, v162, s[40:41]
	v_lshlrev_b32_e32 v170, 16, v155
	v_fmac_f32_e32 v162, v154, v170
	v_and_b32_e32 v154, 0xffff0000, v163
	v_add_f32_e32 v154, v251, v154
	v_mul_f32_e32 v154, 0xbfb8aa3b, v154
	v_exp_f32_e32 v154, v154
	v_and_b32_e32 v159, 0xffff0000, v159
	v_cndmask_b32_e64 v159, 0, v159, s[40:41]
	v_and_b32_e32 v155, 0xffff0000, v155
	v_add_f32_e32 v154, 1.0, v154
	v_rcp_f32_e32 v154, v154
	s_nop 0
	v_fmac_f32_e32 v159, v154, v155
	v_lshlrev_b32_e32 v154, 16, v164
	v_add_f32_e32 v154, v238, v154
	v_mul_f32_e32 v154, 0xbfb8aa3b, v154
	v_exp_f32_e32 v154, v154
	v_lshlrev_b32_e32 v155, 16, v160
	v_cndmask_b32_e64 v163, 0, v155, s[40:41]
	v_lshlrev_b32_e32 v155, 16, v156
	v_add_f32_e32 v154, 1.0, v154
	v_rcp_f32_e32 v154, v154
	s_nop 0
	v_fmac_f32_e32 v163, v154, v155
	v_and_b32_e32 v154, 0xffff0000, v164
	v_add_f32_e32 v154, v239, v154
	v_mul_f32_e32 v154, 0xbfb8aa3b, v154
	v_exp_f32_e32 v154, v154
	v_and_b32_e32 v155, 0xffff0000, v160
	v_cndmask_b32_e64 v160, 0, v155, s[40:41]
	v_and_b32_e32 v155, 0xffff0000, v156
	v_add_f32_e32 v154, 1.0, v154
	v_rcp_f32_e32 v154, v154
	s_nop 0
	v_fmac_f32_e32 v160, v154, v155
	v_lshlrev_b32_e32 v154, 16, v165
	v_add_f32_e32 v154, v240, v154
	v_mul_f32_e32 v154, 0xbfb8aa3b, v154
	v_exp_f32_e32 v154, v154
	v_lshlrev_b32_e32 v155, 16, v161
	v_cndmask_b32_e64 v164, 0, v155, s[40:41]
	v_lshlrev_b32_e32 v155, 16, v157
	v_add_f32_e32 v154, 1.0, v154
	v_rcp_f32_e32 v154, v154
	s_nop 0
	v_fmac_f32_e32 v164, v154, v155
	v_and_b32_e32 v154, 0xffff0000, v165
	v_add_f32_e32 v154, v241, v154
	v_mul_f32_e32 v154, 0xbfb8aa3b, v154
; DI float bf2f(short b) { return __uint_as_float(((unsigned)(unsigned short)b) << 16); }
; DI bf16x8 pack8(const float* a) { u32x4 w = {cvtpk(a[0], a[1]), cvtpk(a[2], a[3]), cvtpk(a[4], a[5]), cvtpk(a[6], a[7])}; return *reinterpret_cast<bf16x8*>(&w); }
; DI float sigm(float x) { return __builtin_amdgcn_rcpf(1.f + __builtin_amdgcn_exp2f(-1.4426950408889634f * x)); }
; #define WAIT_L(n) asm volatile("s_waitcnt lgkmcnt(" #n ")":::"memory")
; #define BAR __builtin_amdgcn_s_barrier()
; #define WAIT_L(n) asm volatile("s_waitcnt lgkmcnt(" #n ")":::"memory")
; #define BAR __builtin_amdgcn_s_barrier()
; DI void gemm8_run(const GemmJob& ja, const GemmJob& jb, char* lds) {
;     ...
;           for (int it = 0; it < 4; ++it) { const int idx = (hb * 4 + it) * 512 + tid; const int r = idx >> 5, c16 = idx & 31; const size_t grow = (size_t)(brow + ai * 128 + r);
;             const float4 b0 = *reinterpret_cast<const float4*>(J.bias + bcol + c16 * 8), b1 = *reinterpret_cast<const float4*>(J.bias + bcol + c16 * 8 + 4);
;             const float bb[8] = {b0.x, b0.y, b0.z, b0.w, b1.x, b1.y, b1.z, b1.w};
;             float o8[8];
; #pragma unroll
;             for (int j = 0; j < 8; ++j) { const float g = sigm(bf2f(gv[it][j]) + bb[j]); o8[j] = (gb ? bf2f(ov[it][j]) : 0.f) + bf2f(av[it][j]) * g; }
;             *reinterpret_cast<bf16x8*>(J.C + grow * 1024 + bcol + c16 * 8) = pack8(o8); } }
;         WAIT_L(0); BAR;
	v_exp_f32_e32 v154, v154
	v_and_b32_e32 v155, 0xffff0000, v161
	v_cndmask_b32_e64 v161, 0, v155, s[40:41]
	v_and_b32_e32 v155, 0xffff0000, v157
	v_add_f32_e32 v154, 1.0, v154
	v_rcp_f32_e32 v154, v154
	s_nop 0
	v_fmac_f32_e32 v161, v154, v155
	v_cvt_pk_bf16_f32 v154, v174, v158
	v_cvt_pk_bf16_f32 v155, v162, v159
	v_lshl_add_u64 v[158:159], v[182:183], 0, v[194:195]
	v_cvt_pk_bf16_f32 v156, v163, v160
	v_cvt_pk_bf16_f32 v157, v164, v161
	global_store_dwordx4 v[158:159], v[154:157], off
	s_nop 0
	v_lshlrev_b32_e32 v162, 16, v150
	v_and_b32_e32 v150, 0xffff0000, v150
	v_lshlrev_b32_e32 v163, 16, v142
	v_and_b32_e32 v142, 0xffff0000, v142
	v_add_f32_e32 v150, v249, v150
	v_mul_f32_e32 v150, 0xbfb8aa3b, v150
	v_exp_f32_e32 v150, v150
	v_add_f32_e32 v158, v248, v162
	v_lshlrev_b32_e32 v162, 16, v146
	v_and_b32_e32 v146, 0xffff0000, v146
	v_add_f32_e32 v150, 1.0, v150
	v_rcp_f32_e32 v150, v150
	v_cndmask_b32_e64 v146, 0, v146, s[40:41]
	v_mul_f32_e32 v158, 0xbfb8aa3b, v158
	v_exp_f32_e32 v158, v158
	v_fmac_f32_e32 v146, v150, v142
	v_lshlrev_b32_e32 v142, 16, v151
	v_add_f32_e32 v142, v250, v142
	v_mul_f32_e32 v142, 0xbfb8aa3b, v142
	v_exp_f32_e32 v142, v142
	v_add_f32_e32 v158, 1.0, v158
	v_rcp_f32_e32 v158, v158
	v_cndmask_b32_e64 v162, 0, v162, s[40:41]
	v_add_f32_e32 v142, 1.0, v142
	v_rcp_f32_e32 v142, v142
	v_lshlrev_b32_e32 v150, 16, v147
	v_fmac_f32_e32 v162, v158, v163
	v_cndmask_b32_e64 v150, 0, v150, s[40:41]
	v_lshlrev_b32_e32 v158, 16, v143
	v_fmac_f32_e32 v150, v142, v158
	v_and_b32_e32 v142, 0xffff0000, v151
	v_add_f32_e32 v142, v251, v142
	v_mul_f32_e32 v142, 0xbfb8aa3b, v142
	v_exp_f32_e32 v142, v142
	v_and_b32_e32 v147, 0xffff0000, v147
	v_cndmask_b32_e64 v147, 0, v147, s[40:41]
	v_and_b32_e32 v143, 0xffff0000, v143
	v_add_f32_e32 v142, 1.0, v142
	v_rcp_f32_e32 v142, v142
	s_nop 0
	v_fmac_f32_e32 v147, v142, v143
	v_lshlrev_b32_e32 v142, 16, v152
	v_add_f32_e32 v142, v238, v142
	v_mul_f32_e32 v142, 0xbfb8aa3b, v142
	v_exp_f32_e32 v142, v142
	v_lshlrev_b32_e32 v143, 16, v148
	v_cndmask_b32_e64 v151, 0, v143, s[40:41]
	v_lshlrev_b32_e32 v143, 16, v144
	v_add_f32_e32 v142, 1.0, v142
	v_rcp_f32_e32 v142, v142
	s_nop 0
	v_fmac_f32_e32 v151, v142, v143
	v_and_b32_e32 v142, 0xffff0000, v152
	v_add_f32_e32 v142, v239, v142
	v_mul_f32_e32 v142, 0xbfb8aa3b, v142
	v_exp_f32_e32 v142, v142
	v_and_b32_e32 v143, 0xffff0000, v148
	v_cndmask_b32_e64 v148, 0, v143, s[40:41]
	v_and_b32_e32 v143, 0xffff0000, v144
	v_add_f32_e32 v142, 1.0, v142
	v_rcp_f32_e32 v142, v142
	s_nop 0
	v_fmac_f32_e32 v148, v142, v143
	v_lshlrev_b32_e32 v142, 16, v153
	v_add_f32_e32 v142, v240, v142
	v_mul_f32_e32 v142, 0xbfb8aa3b, v142
	v_exp_f32_e32 v142, v142
	v_lshlrev_b32_e32 v143, 16, v149
	v_cndmask_b32_e64 v152, 0, v143, s[40:41]
	v_lshlrev_b32_e32 v143, 16, v145
	v_add_f32_e32 v142, 1.0, v142
	v_rcp_f32_e32 v142, v142
	s_nop 0
	v_fmac_f32_e32 v152, v142, v143
	v_and_b32_e32 v142, 0xffff0000, v153
	v_add_f32_e32 v142, v241, v142
	v_mul_f32_e32 v142, 0xbfb8aa3b, v142
	v_exp_f32_e32 v142, v142
	v_and_b32_e32 v143, 0xffff0000, v149
	v_cndmask_b32_e64 v149, 0, v143, s[40:41]
	v_and_b32_e32 v143, 0xffff0000, v145
	v_add_f32_e32 v142, 1.0, v142
	v_rcp_f32_e32 v142, v142
	s_nop 0
	v_fmac_f32_e32 v149, v142, v143
	v_cvt_pk_bf16_f32 v142, v162, v146
	v_cvt_pk_bf16_f32 v143, v150, v147
	v_lshl_add_u64 v[146:147], v[182:183], 0, v[192:193]
	v_cvt_pk_bf16_f32 v144, v151, v148
	v_cvt_pk_bf16_f32 v145, v152, v149
	global_store_dwordx4 v[146:147], v[142:145], off
	s_nop 0
	v_lshlrev_b32_e32 v150, 16, v138
	v_and_b32_e32 v138, 0xffff0000, v138
	v_lshlrev_b32_e32 v151, 16, v130
	v_and_b32_e32 v130, 0xffff0000, v130
	v_add_f32_e32 v138, v249, v138
	v_mul_f32_e32 v138, 0xbfb8aa3b, v138
	v_exp_f32_e32 v138, v138
	v_add_f32_e32 v146, v248, v150
	v_lshlrev_b32_e32 v150, 16, v134
	v_and_b32_e32 v134, 0xffff0000, v134
	v_add_f32_e32 v138, 1.0, v138
	v_rcp_f32_e32 v138, v138
	v_cndmask_b32_e64 v134, 0, v134, s[40:41]
	v_mul_f32_e32 v146, 0xbfb8aa3b, v146
	v_exp_f32_e32 v146, v146
	v_fmac_f32_e32 v134, v138, v130
	v_lshlrev_b32_e32 v130, 16, v139
	v_add_f32_e32 v130, v250, v130
	v_mul_f32_e32 v130, 0xbfb8aa3b, v130
	v_exp_f32_e32 v130, v130
	v_add_f32_e32 v146, 1.0, v146
	v_rcp_f32_e32 v146, v146
	v_cndmask_b32_e64 v150, 0, v150, s[40:41]
	v_add_f32_e32 v130, 1.0, v130
	v_rcp_f32_e32 v130, v130
	v_lshlrev_b32_e32 v138, 16, v135
	v_fmac_f32_e32 v150, v146, v151
	v_cndmask_b32_e64 v138, 0, v138, s[40:41]
	v_lshlrev_b32_e32 v146, 16, v131
	v_fmac_f32_e32 v138, v130, v146
	v_and_b32_e32 v130, 0xffff0000, v139
	v_add_f32_e32 v130, v251, v130
	v_mul_f32_e32 v130, 0xbfb8aa3b, v130
	v_exp_f32_e32 v130, v130
	v_and_b32_e32 v135, 0xffff0000, v135
	v_cndmask_b32_e64 v135, 0, v135, s[40:41]
	v_and_b32_e32 v131, 0xffff0000, v131
	v_add_f32_e32 v130, 1.0, v130
	v_rcp_f32_e32 v130, v130
	s_nop 0
	v_fmac_f32_e32 v135, v130, v131
	v_lshlrev_b32_e32 v130, 16, v140
	v_add_f32_e32 v130, v238, v130
	v_mul_f32_e32 v130, 0xbfb8aa3b, v130
	v_exp_f32_e32 v130, v130
	v_lshlrev_b32_e32 v131, 16, v136
	v_cndmask_b32_e64 v139, 0, v131, s[40:41]
	v_lshlrev_b32_e32 v131, 16, v132
	v_add_f32_e32 v130, 1.0, v130
	v_rcp_f32_e32 v130, v130
	s_nop 0
	v_fmac_f32_e32 v139, v130, v131
	v_and_b32_e32 v130, 0xffff0000, v140
	v_add_f32_e32 v130, v239, v130
	v_mul_f32_e32 v130, 0xbfb8aa3b, v130
	v_exp_f32_e32 v130, v130
	v_and_b32_e32 v131, 0xffff0000, v136
	v_cndmask_b32_e64 v136, 0, v131, s[40:41]
	v_and_b32_e32 v131, 0xffff0000, v132
	v_add_f32_e32 v130, 1.0, v130
	v_rcp_f32_e32 v130, v130
	s_nop 0
	v_fmac_f32_e32 v136, v130, v131
	v_lshlrev_b32_e32 v130, 16, v141
	v_add_f32_e32 v130, v240, v130
	v_mul_f32_e32 v130, 0xbfb8aa3b, v130
	v_exp_f32_e32 v130, v130
	v_lshlrev_b32_e32 v131, 16, v137
	v_cndmask_b32_e64 v140, 0, v131, s[40:41]
	v_lshlrev_b32_e32 v131, 16, v133
	v_add_f32_e32 v130, 1.0, v130
	v_rcp_f32_e32 v130, v130
	s_nop 0
	v_fmac_f32_e32 v140, v130, v131
	v_and_b32_e32 v130, 0xffff0000, v141
	v_add_f32_e32 v130, v241, v130
	v_mul_f32_e32 v130, 0xbfb8aa3b, v130
	v_exp_f32_e32 v130, v130
	v_and_b32_e32 v131, 0xffff0000, v137
	v_cndmask_b32_e64 v137, 0, v131, s[40:41]
	v_and_b32_e32 v131, 0xffff0000, v133
	v_add_f32_e32 v130, 1.0, v130
	v_rcp_f32_e32 v130, v130
	s_nop 0
	v_fmac_f32_e32 v137, v130, v131
	v_cvt_pk_bf16_f32 v130, v150, v134
	v_cvt_pk_bf16_f32 v131, v138, v135
	v_lshl_add_u64 v[134:135], v[182:183], 0, v[190:191]
	v_cvt_pk_bf16_f32 v132, v139, v136
	v_cvt_pk_bf16_f32 v133, v140, v137
	global_store_dwordx4 v[134:135], v[130:133], off
	s_waitcnt lgkmcnt(0)
	s_barrier
; DI uint2 pack4(float a, float b, float c, float d) { return make_uint2(cvtpk(a, b), cvtpk(c, d)); }
; #define WAIT_L(n) asm volatile("s_waitcnt lgkmcnt(" #n ")":::"memory")
; #define BAR __builtin_amdgcn_s_barrier()
; #define WAIT_L(n) asm volatile("s_waitcnt lgkmcnt(" #n ")":::"memory")
; #define BAR __builtin_amdgcn_s_barrier()
; DI void gemm8_run(const GemmJob& ja, const GemmJob& jb, char* lds) {
;     ...
;       for (int ai = 0; ai < 2; ++ai) {
; #pragma unroll
;         for (int bj = 0; bj < 2; ++bj) {
; #pragma unroll
;           for (int m = 0; m < 4; ++m) {
; #pragma unroll
;             for (int n = 0; n < 2; ++n)
;               *reinterpret_cast<uint2*>(lds + (wr * 64 + m * 16 + fr) * 528 + (bj * 128 + wc * 32 + n * 16 + fq * 4) * 2) =
;                 pack4(acc[ai][bj][m][n][0], acc[ai][bj][m][n][1], acc[ai][bj][m][n][2], acc[ai][bj][m][n][3]); } }
;         WAIT_L(0); BAR;
; #pragma unroll
;         for (int hb = 0; hb < 2; ++hb) {
;           bf16x8 av[4], gv[4], ov[4];
; #pragma unroll
;           for (int it = 0; it < 4; ++it) { const int idx = (hb * 4 + it) * 512 + tid; const int r = idx >> 5, c16 = idx & 31; const size_t grow = (size_t)(brow + ai * 128 + r);
;             av[it] = *reinterpret_cast<const bf16x8*>(lds + r * 528 + c16 * 16);
;             gv[it] = ld8(J.gsrc + grow * INP + bcol + c16 * 8);
;             if (gb) ov[it] = ld8(J.C + grow * 1024 + bcol + c16 * 8); else ov[it] = av[it]; }
	s_nop 0
	v_cvt_pk_bf16_f32 v130, v60, v61
	v_cvt_pk_bf16_f32 v131, v62, v63
	ds_write_b64 v205, v[130:131]
	v_cvt_pk_bf16_f32 v130, v56, v57
	v_cvt_pk_bf16_f32 v131, v58, v59
	ds_write_b64 v205, v[130:131] offset:32
	v_cvt_pk_bf16_f32 v130, v52, v53
	v_cvt_pk_bf16_f32 v131, v54, v55
	ds_write_b64 v205, v[130:131] offset:8448
	v_cvt_pk_bf16_f32 v130, v48, v49
	v_cvt_pk_bf16_f32 v131, v50, v51
	ds_write_b64 v205, v[130:131] offset:8480
	v_cvt_pk_bf16_f32 v130, v44, v45
	v_cvt_pk_bf16_f32 v131, v46, v47
	ds_write_b64 v205, v[130:131] offset:16896
	v_cvt_pk_bf16_f32 v130, v40, v41
	v_cvt_pk_bf16_f32 v131, v42, v43
	ds_write_b64 v205, v[130:131] offset:16928
	v_cvt_pk_bf16_f32 v130, v36, v37
	v_cvt_pk_bf16_f32 v131, v38, v39
	ds_write_b64 v205, v[130:131] offset:25344
	v_cvt_pk_bf16_f32 v130, v32, v33
	v_cvt_pk_bf16_f32 v131, v34, v35
	ds_write_b64 v205, v[130:131] offset:25376
	v_cvt_pk_bf16_f32 v130, v28, v29
	v_cvt_pk_bf16_f32 v131, v30, v31
	ds_write_b64 v205, v[130:131] offset:256
	v_cvt_pk_bf16_f32 v130, v24, v25
	v_cvt_pk_bf16_f32 v131, v26, v27
	ds_write_b64 v205, v[130:131] offset:288
	v_cvt_pk_bf16_f32 v130, v20, v21
	v_cvt_pk_bf16_f32 v131, v22, v23
	ds_write_b64 v205, v[130:131] offset:8704
	v_cvt_pk_bf16_f32 v130, v16, v17
	v_cvt_pk_bf16_f32 v131, v18, v19
	ds_write_b64 v205, v[130:131] offset:8736
	v_cvt_pk_bf16_f32 v130, v12, v13
	v_cvt_pk_bf16_f32 v131, v14, v15
	ds_write_b64 v205, v[130:131] offset:17152
	v_cvt_pk_bf16_f32 v130, v8, v9
	v_cvt_pk_bf16_f32 v131, v10, v11
	ds_write_b64 v205, v[130:131] offset:17184
	v_cvt_pk_bf16_f32 v130, v4, v5
	v_cvt_pk_bf16_f32 v131, v6, v7
	ds_write_b64 v205, v[130:131] offset:25600
	v_cvt_pk_bf16_f32 v130, v0, v1
	v_cvt_pk_bf16_f32 v131, v2, v3
	ds_write_b64 v205, v[130:131] offset:25632
	v_add_u32_e32 v130, s95, v207
	v_mad_i64_i32 v[132:133], s[78:79], v130, s33, v[186:187]
	s_waitcnt lgkmcnt(0)
	s_barrier
	global_load_dwordx4 v[174:177], v[132:133], off
	ds_read_b128 v[166:169], v212
	v_ashrrev_i32_e32 v131, 31, v130
	v_lshlrev_b64 v[196:197], 11, v[130:131]
	s_waitcnt lgkmcnt(0)
	v_mov_b64_e32 v[172:173], v[168:169]
	v_mov_b64_e32 v[170:171], v[166:167]
	s_cbranch_vccnz .LBB0_239
	v_lshl_add_u64 v[130:131], v[188:189], 0, v[196:197]
	global_load_dwordx4 v[170:173], v[130:131], off

; DI float bf2f(short b) { return __uint_as_float(((unsigned)(unsigned short)b) << 16); }
; DI bf16x8 pack8(const float* a) { u32x4 w = {cvtpk(a[0], a[1]), cvtpk(a[2], a[3]), cvtpk(a[4], a[5]), cvtpk(a[6], a[7])}; return *reinterpret_cast<bf16x8*>(&w); }
; DI float sigm(float x) { return __builtin_amdgcn_rcpf(1.f + __builtin_amdgcn_exp2f(-1.4426950408889634f * x)); }
; DI void gemm8_run(const GemmJob& ja, const GemmJob& jb, char* lds) {
;     ...
;           for (int it = 0; it < 4; ++it) { const int idx = (hb * 4 + it) * 512 + tid; const int r = idx >> 5, c16 = idx & 31; const size_t grow = (size_t)(brow + ai * 128 + r);
;             const float4 b0 = *reinterpret_cast<const float4*>(J.bias + bcol + c16 * 8), b1 = *reinterpret_cast<const float4*>(J.bias + bcol + c16 * 8 + 4);
;             const float bb[8] = {b0.x, b0.y, b0.z, b0.w, b1.x, b1.y, b1.z, b1.w};
;             float o8[8];
; #pragma unroll
;             for (int j = 0; j < 8; ++j) { const float g = sigm(bf2f(gv[it][j]) + bb[j]); o8[j] = (gb ? bf2f(ov[it][j]) : 0.f) + bf2f(av[it][j]) * g; }
;             *reinterpret_cast<bf16x8*>(J.C + grow * 1024 + bcol + c16 * 8) = pack8(o8); } }
.LBB0_245:
	s_nop 0
	s_waitcnt vmcnt(3)
	v_lshlrev_b32_e32 v205, 16, v174
	v_and_b32_e32 v174, 0xffff0000, v174
	v_lshlrev_b32_e32 v210, 16, v166
	v_and_b32_e32 v166, 0xffff0000, v166
	s_and_b64 vcc, exec, s[42:43]
	s_waitcnt vmcnt(0)
	v_add_f32_e32 v174, v249, v174
	v_mul_f32_e32 v174, 0xbfb8aa3b, v174
	v_exp_f32_e32 v174, v174
	v_add_f32_e32 v205, v248, v205
	v_lshlrev_b32_e32 v206, 16, v170
	v_and_b32_e32 v170, 0xffff0000, v170
	v_add_f32_e32 v174, 1.0, v174
	v_rcp_f32_e32 v174, v174
	v_cndmask_b32_e64 v170, 0, v170, s[40:41]
	v_mul_f32_e32 v205, 0xbfb8aa3b, v205
	v_exp_f32_e32 v205, v205
	v_fmac_f32_e32 v170, v174, v166
	v_lshlrev_b32_e32 v166, 16, v175
	v_add_f32_e32 v166, v250, v166
	v_mul_f32_e32 v166, 0xbfb8aa3b, v166
	v_exp_f32_e32 v166, v166
	v_add_f32_e32 v205, 1.0, v205
	v_rcp_f32_e32 v205, v205
	v_cndmask_b32_e64 v206, 0, v206, s[40:41]
	v_add_f32_e32 v166, 1.0, v166
	v_rcp_f32_e32 v166, v166
	v_lshlrev_b32_e32 v174, 16, v171
	v_fmac_f32_e32 v206, v205, v210
	v_cndmask_b32_e64 v174, 0, v174, s[40:41]
	v_lshlrev_b32_e32 v205, 16, v167
	v_fmac_f32_e32 v174, v166, v205
	v_and_b32_e32 v166, 0xffff0000, v175
	v_add_f32_e32 v166, v251, v166
	v_mul_f32_e32 v166, 0xbfb8aa3b, v166
	v_exp_f32_e32 v166, v166
	v_and_b32_e32 v171, 0xffff0000, v171
	v_cndmask_b32_e64 v171, 0, v171, s[40:41]
	v_and_b32_e32 v167, 0xffff0000, v167
	v_add_f32_e32 v166, 1.0, v166
	v_rcp_f32_e32 v166, v166
	s_nop 0
	v_fmac_f32_e32 v171, v166, v167
	v_lshlrev_b32_e32 v166, 16, v176
	v_add_f32_e32 v166, v238, v166
	v_mul_f32_e32 v166, 0xbfb8aa3b, v166
	v_exp_f32_e32 v166, v166
	v_lshlrev_b32_e32 v167, 16, v172
	v_cndmask_b32_e64 v175, 0, v167, s[40:41]
	v_lshlrev_b32_e32 v167, 16, v168
	v_add_f32_e32 v166, 1.0, v166
	v_rcp_f32_e32 v166, v166
	s_nop 0
	v_fmac_f32_e32 v175, v166, v167
	v_and_b32_e32 v166, 0xffff0000, v176
	v_add_f32_e32 v166, v239, v166
	v_mul_f32_e32 v166, 0xbfb8aa3b, v166
	v_exp_f32_e32 v166, v166
	v_and_b32_e32 v167, 0xffff0000, v172
	v_cndmask_b32_e64 v172, 0, v167, s[40:41]
	v_and_b32_e32 v167, 0xffff0000, v168
	v_add_f32_e32 v166, 1.0, v166
	v_rcp_f32_e32 v166, v166
	s_nop 0
	v_fmac_f32_e32 v172, v166, v167
	v_lshlrev_b32_e32 v166, 16, v177
	v_add_f32_e32 v166, v240, v166
	v_mul_f32_e32 v166, 0xbfb8aa3b, v166
	v_exp_f32_e32 v166, v166
	v_lshlrev_b32_e32 v167, 16, v173
	v_cndmask_b32_e64 v176, 0, v167, s[40:41]
	v_lshlrev_b32_e32 v167, 16, v169
	v_add_f32_e32 v166, 1.0, v166
	v_rcp_f32_e32 v166, v166
	s_nop 0
	v_fmac_f32_e32 v176, v166, v167
	v_and_b32_e32 v166, 0xffff0000, v177
	v_add_f32_e32 v166, v241, v166
	v_mul_f32_e32 v166, 0xbfb8aa3b, v166
	v_exp_f32_e32 v166, v166
	v_and_b32_e32 v167, 0xffff0000, v173
	v_cndmask_b32_e64 v173, 0, v167, s[40:41]
	v_and_b32_e32 v167, 0xffff0000, v169
	v_add_f32_e32 v166, 1.0, v166
	v_rcp_f32_e32 v166, v166
	s_nop 0
	v_fmac_f32_e32 v173, v166, v167
	v_cvt_pk_bf16_f32 v166, v206, v170
	v_cvt_pk_bf16_f32 v167, v174, v171
	v_lshl_add_u64 v[170:171], v[182:183], 0, v[196:197]
	v_cvt_pk_bf16_f32 v168, v175, v172
	v_cvt_pk_bf16_f32 v169, v176, v173
	global_store_dwordx4 v[170:171], v[166:169], off
	s_nop 0
	v_lshlrev_b32_e32 v174, 16, v162
	v_and_b32_e32 v162, 0xffff0000, v162
	v_lshlrev_b32_e32 v175, 16, v154
	v_and_b32_e32 v154, 0xffff0000, v154
	v_add_f32_e32 v162, v249, v162
	v_mul_f32_e32 v162, 0xbfb8aa3b, v162
	v_exp_f32_e32 v162, v162
	v_add_f32_e32 v170, v248, v174
	v_lshlrev_b32_e32 v174, 16, v158
	v_and_b32_e32 v158, 0xffff0000, v158
	v_add_f32_e32 v162, 1.0, v162
	v_rcp_f32_e32 v162, v162
	v_cndmask_b32_e64 v158, 0, v158, s[40:41]
	v_mul_f32_e32 v170, 0xbfb8aa3b, v170
	v_exp_f32_e32 v170, v170
	v_fmac_f32_e32 v158, v162, v154
	v_lshlrev_b32_e32 v154, 16, v163
	v_add_f32_e32 v154, v250, v154
	v_mul_f32_e32 v154, 0xbfb8aa3b, v154
	v_exp_f32_e32 v154, v154
	v_add_f32_e32 v170, 1.0, v170
	v_rcp_f32_e32 v170, v170
	v_cndmask_b32_e64 v174, 0, v174, s[40:41]
	v_add_f32_e32 v154, 1.0, v154
	v_rcp_f32_e32 v154, v154
	v_lshlrev_b32_e32 v162, 16, v159
	v_fmac_f32_e32 v174, v170, v175
	v_cndmask_b32_e64 v162, 0, v162, s[40:41]
	v_lshlrev_b32_e32 v170, 16, v155
	v_fmac_f32_e32 v162, v154, v170
	v_and_b32_e32 v154, 0xffff0000, v163
	v_add_f32_e32 v154, v251, v154
	v_mul_f32_e32 v154, 0xbfb8aa3b, v154
	v_exp_f32_e32 v154, v154
	v_and_b32_e32 v159, 0xffff0000, v159
	v_cndmask_b32_e64 v159, 0, v159, s[40:41]
	v_and_b32_e32 v155, 0xffff0000, v155
	v_add_f32_e32 v154, 1.0, v154
	v_rcp_f32_e32 v154, v154
	s_nop 0
	v_fmac_f32_e32 v159, v154, v155
	v_lshlrev_b32_e32 v154, 16, v164
	v_add_f32_e32 v154, v238, v154
	v_mul_f32_e32 v154, 0xbfb8aa3b, v154
	v_exp_f32_e32 v154, v154
	v_lshlrev_b32_e32 v155, 16, v160
	v_cndmask_b32_e64 v163, 0, v155, s[40:41]
	v_lshlrev_b32_e32 v155, 16, v156
	v_add_f32_e32 v154, 1.0, v154
	v_rcp_f32_e32 v154, v154
	s_nop 0
	v_fmac_f32_e32 v163, v154, v155
	v_and_b32_e32 v154, 0xffff0000, v164
	v_add_f32_e32 v154, v239, v154
	v_mul_f32_e32 v154, 0xbfb8aa3b, v154
	v_exp_f32_e32 v154, v154
	v_and_b32_e32 v155, 0xffff0000, v160
	v_cndmask_b32_e64 v160, 0, v155, s[40:41]
	v_and_b32_e32 v155, 0xffff0000, v156
	v_add_f32_e32 v154, 1.0, v154
	v_rcp_f32_e32 v154, v154
	s_nop 0
	v_fmac_f32_e32 v160, v154, v155
	v_lshlrev_b32_e32 v154, 16, v165
	v_add_f32_e32 v154, v240, v154
	v_mul_f32_e32 v154, 0xbfb8aa3b, v154
	v_exp_f32_e32 v154, v154
	v_lshlrev_b32_e32 v155, 16, v161
	v_cndmask_b32_e64 v164, 0, v155, s[40:41]
	v_lshlrev_b32_e32 v155, 16, v157
	v_add_f32_e32 v154, 1.0, v154
	v_rcp_f32_e32 v154, v154
	s_nop 0
	v_fmac_f32_e32 v164, v154, v155
	v_and_b32_e32 v154, 0xffff0000, v165
	v_add_f32_e32 v154, v241, v154
	v_mul_f32_e32 v154, 0xbfb8aa3b, v154
	v_exp_f32_e32 v154, v154
	v_and_b32_e32 v155, 0xffff0000, v161
; DI float bf2f(short b) { return __uint_as_float(((unsigned)(unsigned short)b) << 16); }
; DI bf16x8 pack8(const float* a) { u32x4 w = {cvtpk(a[0], a[1]), cvtpk(a[2], a[3]), cvtpk(a[4], a[5]), cvtpk(a[6], a[7])}; return *reinterpret_cast<bf16x8*>(&w); }
; DI float sigm(float x) { return __builtin_amdgcn_rcpf(1.f + __builtin_amdgcn_exp2f(-1.4426950408889634f * x)); }
; #define WAIT_L(n) asm volatile("s_waitcnt lgkmcnt(" #n ")":::"memory")
; #define BAR __builtin_amdgcn_s_barrier()
; #define WAIT_L(n) asm volatile("s_waitcnt lgkmcnt(" #n ")":::"memory")
; #define BAR __builtin_amdgcn_s_barrier()
; DI void gemm8_run(const GemmJob& ja, const GemmJob& jb, char* lds) {
;     ...
;           for (int it = 0; it < 4; ++it) { const int idx = (hb * 4 + it) * 512 + tid; const int r = idx >> 5, c16 = idx & 31; const size_t grow = (size_t)(brow + ai * 128 + r);
;             const float4 b0 = *reinterpret_cast<const float4*>(J.bias + bcol + c16 * 8), b1 = *reinterpret_cast<const float4*>(J.bias + bcol + c16 * 8 + 4);
;             const float bb[8] = {b0.x, b0.y, b0.z, b0.w, b1.x, b1.y, b1.z, b1.w};
;             float o8[8];
; #pragma unroll
;             for (int j = 0; j < 8; ++j) { const float g = sigm(bf2f(gv[it][j]) + bb[j]); o8[j] = (gb ? bf2f(ov[it][j]) : 0.f) + bf2f(av[it][j]) * g; }
;             *reinterpret_cast<bf16x8*>(J.C + grow * 1024 + bcol + c16 * 8) = pack8(o8); } }
;         WAIT_L(0); BAR;
	v_cndmask_b32_e64 v161, 0, v155, s[40:41]
	v_and_b32_e32 v155, 0xffff0000, v157
	v_add_f32_e32 v154, 1.0, v154
	v_rcp_f32_e32 v154, v154
	s_nop 0
	v_fmac_f32_e32 v161, v154, v155
	v_cvt_pk_bf16_f32 v154, v174, v158
	v_cvt_pk_bf16_f32 v155, v162, v159
	v_lshl_add_u64 v[158:159], v[182:183], 0, v[194:195]
	v_cvt_pk_bf16_f32 v156, v163, v160
	v_cvt_pk_bf16_f32 v157, v164, v161
	global_store_dwordx4 v[158:159], v[154:157], off
	s_nop 0
	v_lshlrev_b32_e32 v162, 16, v150
	v_and_b32_e32 v150, 0xffff0000, v150
	v_lshlrev_b32_e32 v163, 16, v142
	v_and_b32_e32 v142, 0xffff0000, v142
	v_add_f32_e32 v150, v249, v150
	v_mul_f32_e32 v150, 0xbfb8aa3b, v150
	v_exp_f32_e32 v150, v150
	v_add_f32_e32 v158, v248, v162
	v_lshlrev_b32_e32 v162, 16, v146
	v_and_b32_e32 v146, 0xffff0000, v146
	v_add_f32_e32 v150, 1.0, v150
	v_rcp_f32_e32 v150, v150
	v_cndmask_b32_e64 v146, 0, v146, s[40:41]
	v_mul_f32_e32 v158, 0xbfb8aa3b, v158
	v_exp_f32_e32 v158, v158
	v_fmac_f32_e32 v146, v150, v142
	v_lshlrev_b32_e32 v142, 16, v151
	v_add_f32_e32 v142, v250, v142
	v_mul_f32_e32 v142, 0xbfb8aa3b, v142
	v_exp_f32_e32 v142, v142
	v_add_f32_e32 v158, 1.0, v158
	v_rcp_f32_e32 v158, v158
	v_cndmask_b32_e64 v162, 0, v162, s[40:41]
	v_add_f32_e32 v142, 1.0, v142
	v_rcp_f32_e32 v142, v142
	v_lshlrev_b32_e32 v150, 16, v147
	v_fmac_f32_e32 v162, v158, v163
	v_cndmask_b32_e64 v150, 0, v150, s[40:41]
	v_lshlrev_b32_e32 v158, 16, v143
	v_fmac_f32_e32 v150, v142, v158
	v_and_b32_e32 v142, 0xffff0000, v151
	v_add_f32_e32 v142, v251, v142
	v_mul_f32_e32 v142, 0xbfb8aa3b, v142
	v_exp_f32_e32 v142, v142
	v_and_b32_e32 v147, 0xffff0000, v147
	v_cndmask_b32_e64 v147, 0, v147, s[40:41]
	v_and_b32_e32 v143, 0xffff0000, v143
	v_add_f32_e32 v142, 1.0, v142
	v_rcp_f32_e32 v142, v142
	s_nop 0
	v_fmac_f32_e32 v147, v142, v143
	v_lshlrev_b32_e32 v142, 16, v152
	v_add_f32_e32 v142, v238, v142
	v_mul_f32_e32 v142, 0xbfb8aa3b, v142
	v_exp_f32_e32 v142, v142
	v_lshlrev_b32_e32 v143, 16, v148
	v_cndmask_b32_e64 v151, 0, v143, s[40:41]
	v_lshlrev_b32_e32 v143, 16, v144
	v_add_f32_e32 v142, 1.0, v142
	v_rcp_f32_e32 v142, v142
	s_nop 0
	v_fmac_f32_e32 v151, v142, v143
	v_and_b32_e32 v142, 0xffff0000, v152
	v_add_f32_e32 v142, v239, v142
	v_mul_f32_e32 v142, 0xbfb8aa3b, v142
	v_exp_f32_e32 v142, v142
	v_and_b32_e32 v143, 0xffff0000, v148
	v_cndmask_b32_e64 v148, 0, v143, s[40:41]
	v_and_b32_e32 v143, 0xffff0000, v144
	v_add_f32_e32 v142, 1.0, v142
	v_rcp_f32_e32 v142, v142
	s_nop 0
	v_fmac_f32_e32 v148, v142, v143
	v_lshlrev_b32_e32 v142, 16, v153
	v_add_f32_e32 v142, v240, v142
	v_mul_f32_e32 v142, 0xbfb8aa3b, v142
	v_exp_f32_e32 v142, v142
	v_lshlrev_b32_e32 v143, 16, v149
	v_cndmask_b32_e64 v152, 0, v143, s[40:41]
	v_lshlrev_b32_e32 v143, 16, v145
	v_add_f32_e32 v142, 1.0, v142
	v_rcp_f32_e32 v142, v142
	s_nop 0
	v_fmac_f32_e32 v152, v142, v143
	v_and_b32_e32 v142, 0xffff0000, v153
	v_add_f32_e32 v142, v241, v142
	v_mul_f32_e32 v142, 0xbfb8aa3b, v142
	v_exp_f32_e32 v142, v142
	v_and_b32_e32 v143, 0xffff0000, v149
	v_cndmask_b32_e64 v149, 0, v143, s[40:41]
	v_and_b32_e32 v143, 0xffff0000, v145
	v_add_f32_e32 v142, 1.0, v142
	v_rcp_f32_e32 v142, v142
	s_nop 0
	v_fmac_f32_e32 v149, v142, v143
	v_cvt_pk_bf16_f32 v142, v162, v146
	v_cvt_pk_bf16_f32 v143, v150, v147
	v_lshl_add_u64 v[146:147], v[182:183], 0, v[192:193]
	v_cvt_pk_bf16_f32 v144, v151, v148
	v_cvt_pk_bf16_f32 v145, v152, v149
	global_store_dwordx4 v[146:147], v[142:145], off
	s_nop 0
	v_lshlrev_b32_e32 v150, 16, v138
	v_and_b32_e32 v138, 0xffff0000, v138
	v_lshlrev_b32_e32 v151, 16, v130
	v_and_b32_e32 v130, 0xffff0000, v130
	v_add_f32_e32 v138, v249, v138
	v_mul_f32_e32 v138, 0xbfb8aa3b, v138
	v_exp_f32_e32 v138, v138
	v_add_f32_e32 v146, v248, v150
	v_lshlrev_b32_e32 v150, 16, v134
	v_and_b32_e32 v134, 0xffff0000, v134
	v_add_f32_e32 v138, 1.0, v138
	v_rcp_f32_e32 v138, v138
	v_cndmask_b32_e64 v134, 0, v134, s[40:41]
	v_mul_f32_e32 v146, 0xbfb8aa3b, v146
	v_exp_f32_e32 v146, v146
	v_fmac_f32_e32 v134, v138, v130
	v_lshlrev_b32_e32 v130, 16, v139
	v_add_f32_e32 v130, v250, v130
	v_mul_f32_e32 v130, 0xbfb8aa3b, v130
	v_exp_f32_e32 v130, v130
	v_add_f32_e32 v146, 1.0, v146
	v_rcp_f32_e32 v146, v146
	v_cndmask_b32_e64 v150, 0, v150, s[40:41]
	v_add_f32_e32 v130, 1.0, v130
	v_rcp_f32_e32 v130, v130
	v_lshlrev_b32_e32 v138, 16, v135
	v_fmac_f32_e32 v150, v146, v151
	v_cndmask_b32_e64 v138, 0, v138, s[40:41]
	v_lshlrev_b32_e32 v146, 16, v131
	v_fmac_f32_e32 v138, v130, v146
	v_and_b32_e32 v130, 0xffff0000, v139
	v_add_f32_e32 v130, v251, v130
	v_mul_f32_e32 v130, 0xbfb8aa3b, v130
	v_exp_f32_e32 v130, v130
	v_and_b32_e32 v135, 0xffff0000, v135
	v_cndmask_b32_e64 v135, 0, v135, s[40:41]
	v_and_b32_e32 v131, 0xffff0000, v131
	v_add_f32_e32 v130, 1.0, v130
	v_rcp_f32_e32 v130, v130
	s_nop 0
	v_fmac_f32_e32 v135, v130, v131
	v_lshlrev_b32_e32 v130, 16, v140
	v_add_f32_e32 v130, v238, v130
	v_mul_f32_e32 v130, 0xbfb8aa3b, v130
	v_exp_f32_e32 v130, v130
	v_lshlrev_b32_e32 v131, 16, v136
	v_cndmask_b32_e64 v139, 0, v131, s[40:41]
	v_lshlrev_b32_e32 v131, 16, v132
	v_add_f32_e32 v130, 1.0, v130
	v_rcp_f32_e32 v130, v130
	s_nop 0
	v_fmac_f32_e32 v139, v130, v131
	v_and_b32_e32 v130, 0xffff0000, v140
	v_add_f32_e32 v130, v239, v130
	v_mul_f32_e32 v130, 0xbfb8aa3b, v130
	v_exp_f32_e32 v130, v130
	v_and_b32_e32 v131, 0xffff0000, v136
	v_cndmask_b32_e64 v136, 0, v131, s[40:41]
	v_and_b32_e32 v131, 0xffff0000, v132
	v_add_f32_e32 v130, 1.0, v130
	v_rcp_f32_e32 v130, v130
	s_nop 0
	v_fmac_f32_e32 v136, v130, v131
	v_lshlrev_b32_e32 v130, 16, v141
	v_add_f32_e32 v130, v240, v130
	v_mul_f32_e32 v130, 0xbfb8aa3b, v130
	v_exp_f32_e32 v130, v130
	v_lshlrev_b32_e32 v131, 16, v137
	v_cndmask_b32_e64 v140, 0, v131, s[40:41]
	v_lshlrev_b32_e32 v131, 16, v133
	v_add_f32_e32 v130, 1.0, v130
	v_rcp_f32_e32 v130, v130
	s_nop 0
	v_fmac_f32_e32 v140, v130, v131
	v_and_b32_e32 v130, 0xffff0000, v141
	v_add_f32_e32 v130, v241, v130
	v_mul_f32_e32 v130, 0xbfb8aa3b, v130
	v_exp_f32_e32 v130, v130
	v_and_b32_e32 v131, 0xffff0000, v137
	v_cndmask_b32_e64 v137, 0, v131, s[40:41]
	v_and_b32_e32 v131, 0xffff0000, v133
	v_add_f32_e32 v130, 1.0, v130
	v_rcp_f32_e32 v130, v130
	s_nop 0
	v_fmac_f32_e32 v137, v130, v131
	v_cvt_pk_bf16_f32 v130, v150, v134
	v_cvt_pk_bf16_f32 v131, v138, v135
	v_lshl_add_u64 v[134:135], v[182:183], 0, v[190:191]
	v_cvt_pk_bf16_f32 v132, v139, v136
	v_cvt_pk_bf16_f32 v133, v140, v137
	global_store_dwordx4 v[134:135], v[130:133], off
	ds_read_b128 v[166:169], v204
	s_waitcnt lgkmcnt(0)
	v_mov_b64_e32 v[172:173], v[168:169]
	v_add_u32_e32 v130, s95, v203
	v_mad_i64_i32 v[132:133], s[78:79], v130, s33, v[186:187]
	global_load_dwordx4 v[174:177], v[132:133], off
	v_ashrrev_i32_e32 v131, 31, v130
	v_lshlrev_b64 v[194:195], 11, v[130:131]
	v_mov_b64_e32 v[170:171], v[166:167]
	s_cbranch_vccnz .LBB0_247
	v_lshl_add_u64 v[130:131], v[188:189], 0, v[194:195]
	global_load_dwordx4 v[170:173], v[130:131], off

; DI float bf2f(short b) { return __uint_as_float(((unsigned)(unsigned short)b) << 16); }
; DI bf16x8 pack8(const float* a) { u32x4 w = {cvtpk(a[0], a[1]), cvtpk(a[2], a[3]), cvtpk(a[4], a[5]), cvtpk(a[6], a[7])}; return *reinterpret_cast<bf16x8*>(&w); }
; DI float sigm(float x) { return __builtin_amdgcn_rcpf(1.f + __builtin_amdgcn_exp2f(-1.4426950408889634f * x)); }
; DI void gemm8_run(const GemmJob& ja, const GemmJob& jb, char* lds) {
;     ...
;           for (int it = 0; it < 4; ++it) { const int idx = (hb * 4 + it) * 512 + tid; const int r = idx >> 5, c16 = idx & 31; const size_t grow = (size_t)(brow + ai * 128 + r);
;             const float4 b0 = *reinterpret_cast<const float4*>(J.bias + bcol + c16 * 8), b1 = *reinterpret_cast<const float4*>(J.bias + bcol + c16 * 8 + 4);
;             const float bb[8] = {b0.x, b0.y, b0.z, b0.w, b1.x, b1.y, b1.z, b1.w};
;             float o8[8];
; #pragma unroll
;             for (int j = 0; j < 8; ++j) { const float g = sigm(bf2f(gv[it][j]) + bb[j]); o8[j] = (gb ? bf2f(ov[it][j]) : 0.f) + bf2f(av[it][j]) * g; }
;             *reinterpret_cast<bf16x8*>(J.C + grow * 1024 + bcol + c16 * 8) = pack8(o8); } }
.LBB0_253:
	s_nop 0
	s_waitcnt vmcnt(3)
	v_lshlrev_b32_e32 v96, 16, v174
	v_lshlrev_b32_e32 v188, 16, v170
	v_cndmask_b32_e64 v188, 0, v188, s[40:41]
	v_lshlrev_b32_e32 v189, 16, v166
	v_and_b32_e32 v170, 0xffff0000, v170
	v_cndmask_b32_e64 v170, 0, v170, s[40:41]
	v_and_b32_e32 v166, 0xffff0000, v166
	s_waitcnt vmcnt(0)
	v_add_f32_e32 v96, v248, v96
	v_mul_f32_e32 v96, 0xbfb8aa3b, v96
	v_exp_f32_e32 v96, v96
	s_nop 0
	v_add_f32_e32 v96, 1.0, v96
	v_rcp_f32_e32 v96, v96
	s_nop 0
	v_fmac_f32_e32 v188, v96, v189
	v_and_b32_e32 v96, 0xffff0000, v174
	v_add_f32_e32 v96, v249, v96
	v_mul_f32_e32 v96, 0xbfb8aa3b, v96
	v_exp_f32_e32 v96, v96
	s_nop 0
	v_add_f32_e32 v96, 1.0, v96
	v_rcp_f32_e32 v96, v96
	s_nop 0
	v_fmac_f32_e32 v170, v96, v166
	v_lshlrev_b32_e32 v96, 16, v175
	v_add_f32_e32 v96, v250, v96
	v_mul_f32_e32 v96, 0xbfb8aa3b, v96
	v_exp_f32_e32 v96, v96
	v_lshlrev_b32_e32 v166, 16, v171
	v_cndmask_b32_e64 v174, 0, v166, s[40:41]
	v_lshlrev_b32_e32 v166, 16, v167
	v_add_f32_e32 v96, 1.0, v96
	v_rcp_f32_e32 v96, v96
	s_nop 0
	v_fmac_f32_e32 v174, v96, v166
	v_and_b32_e32 v96, 0xffff0000, v175
	v_add_f32_e32 v96, v251, v96
	v_mul_f32_e32 v96, 0xbfb8aa3b, v96
	v_exp_f32_e32 v96, v96
	v_and_b32_e32 v166, 0xffff0000, v171
	v_cndmask_b32_e64 v171, 0, v166, s[40:41]
	v_and_b32_e32 v166, 0xffff0000, v167
	v_add_f32_e32 v96, 1.0, v96
	v_rcp_f32_e32 v96, v96
	s_nop 0
	v_fmac_f32_e32 v171, v96, v166
	v_lshlrev_b32_e32 v96, 16, v176
	v_add_f32_e32 v96, v238, v96
	v_mul_f32_e32 v96, 0xbfb8aa3b, v96
	v_exp_f32_e32 v96, v96
	v_lshlrev_b32_e32 v166, 16, v172
	v_cndmask_b32_e64 v175, 0, v166, s[40:41]
	v_lshlrev_b32_e32 v166, 16, v168
	v_add_f32_e32 v96, 1.0, v96
	v_rcp_f32_e32 v96, v96
	s_nop 0
	v_fmac_f32_e32 v175, v96, v166
	v_and_b32_e32 v96, 0xffff0000, v176
	v_add_f32_e32 v96, v239, v96
	v_mul_f32_e32 v96, 0xbfb8aa3b, v96
	v_exp_f32_e32 v96, v96
	v_and_b32_e32 v166, 0xffff0000, v172
	v_cndmask_b32_e64 v172, 0, v166, s[40:41]
	v_and_b32_e32 v166, 0xffff0000, v168
	v_add_f32_e32 v96, 1.0, v96
	v_rcp_f32_e32 v96, v96
	s_nop 0
	v_fmac_f32_e32 v172, v96, v166
	v_lshlrev_b32_e32 v96, 16, v177
	v_add_f32_e32 v96, v240, v96
	v_mul_f32_e32 v96, 0xbfb8aa3b, v96
	v_exp_f32_e32 v96, v96
	v_lshlrev_b32_e32 v166, 16, v173
	v_cndmask_b32_e64 v176, 0, v166, s[40:41]
	v_lshlrev_b32_e32 v166, 16, v169
	v_add_f32_e32 v96, 1.0, v96
	v_rcp_f32_e32 v96, v96
	s_nop 0
	v_fmac_f32_e32 v176, v96, v166
	v_and_b32_e32 v96, 0xffff0000, v177
	v_add_f32_e32 v96, v241, v96
	v_mul_f32_e32 v96, 0xbfb8aa3b, v96
	v_exp_f32_e32 v96, v96
	v_and_b32_e32 v166, 0xffff0000, v173
	v_cndmask_b32_e64 v173, 0, v166, s[40:41]
	v_and_b32_e32 v166, 0xffff0000, v169
	v_add_f32_e32 v96, 1.0, v96
	v_rcp_f32_e32 v96, v96
	s_nop 0
	v_fmac_f32_e32 v173, v96, v166
	v_cvt_pk_bf16_f32 v166, v188, v170
	v_cvt_pk_bf16_f32 v167, v174, v171
	v_lshl_add_u64 v[170:171], v[182:183], 0, v[194:195]
	v_cvt_pk_bf16_f32 v168, v175, v172
	v_cvt_pk_bf16_f32 v169, v176, v173
	global_store_dwordx4 v[170:171], v[166:169], off
	s_nop 0
	v_lshlrev_b32_e32 v96, 16, v162
	v_lshlrev_b32_e32 v174, 16, v154
	v_and_b32_e32 v154, 0xffff0000, v154
	v_add_f32_e32 v96, v248, v96
	v_mul_f32_e32 v96, 0xbfb8aa3b, v96
	v_exp_f32_e32 v96, v96
	v_lshlrev_b32_e32 v170, 16, v158
	v_cndmask_b32_e64 v170, 0, v170, s[40:41]
	v_and_b32_e32 v158, 0xffff0000, v158
	v_add_f32_e32 v96, 1.0, v96
	v_rcp_f32_e32 v96, v96
	v_cndmask_b32_e64 v158, 0, v158, s[40:41]
	v_fmac_f32_e32 v170, v96, v174
	v_and_b32_e32 v96, 0xffff0000, v162
	v_add_f32_e32 v96, v249, v96
	v_mul_f32_e32 v96, 0xbfb8aa3b, v96
	v_exp_f32_e32 v96, v96
	s_nop 0
	v_add_f32_e32 v96, 1.0, v96
	v_rcp_f32_e32 v96, v96
	s_nop 0
	v_fmac_f32_e32 v158, v96, v154
	v_lshlrev_b32_e32 v96, 16, v163
	v_add_f32_e32 v96, v250, v96
	v_mul_f32_e32 v96, 0xbfb8aa3b, v96
	v_exp_f32_e32 v96, v96
	v_lshlrev_b32_e32 v154, 16, v159
	v_cndmask_b32_e64 v162, 0, v154, s[40:41]
	v_lshlrev_b32_e32 v154, 16, v155
	v_add_f32_e32 v96, 1.0, v96
	v_rcp_f32_e32 v96, v96
	s_nop 0
	v_fmac_f32_e32 v162, v96, v154
	v_and_b32_e32 v96, 0xffff0000, v163
	v_add_f32_e32 v96, v251, v96
	v_mul_f32_e32 v96, 0xbfb8aa3b, v96
	v_exp_f32_e32 v96, v96
	v_and_b32_e32 v154, 0xffff0000, v159
	v_cndmask_b32_e64 v159, 0, v154, s[40:41]
	v_and_b32_e32 v154, 0xffff0000, v155
	v_add_f32_e32 v96, 1.0, v96
	v_rcp_f32_e32 v96, v96
	s_nop 0
	v_fmac_f32_e32 v159, v96, v154
	v_lshlrev_b32_e32 v96, 16, v164
	v_add_f32_e32 v96, v238, v96
	v_mul_f32_e32 v96, 0xbfb8aa3b, v96
	v_exp_f32_e32 v96, v96
	v_lshlrev_b32_e32 v154, 16, v160
	v_cndmask_b32_e64 v163, 0, v154, s[40:41]
	v_lshlrev_b32_e32 v154, 16, v156
	v_add_f32_e32 v96, 1.0, v96
	v_rcp_f32_e32 v96, v96
	s_nop 0
	v_fmac_f32_e32 v163, v96, v154
	v_and_b32_e32 v96, 0xffff0000, v164
	v_add_f32_e32 v96, v239, v96
	v_mul_f32_e32 v96, 0xbfb8aa3b, v96
	v_exp_f32_e32 v96, v96
	v_and_b32_e32 v154, 0xffff0000, v160
	v_cndmask_b32_e64 v160, 0, v154, s[40:41]
	v_and_b32_e32 v154, 0xffff0000, v156
	v_add_f32_e32 v96, 1.0, v96
	v_rcp_f32_e32 v96, v96
	s_nop 0
	v_fmac_f32_e32 v160, v96, v154
	v_lshlrev_b32_e32 v96, 16, v165
	v_add_f32_e32 v96, v240, v96
	v_mul_f32_e32 v96, 0xbfb8aa3b, v96
	v_exp_f32_e32 v96, v96
	v_lshlrev_b32_e32 v154, 16, v161
	v_cndmask_b32_e64 v164, 0, v154, s[40:41]
	v_lshlrev_b32_e32 v154, 16, v157
	v_add_f32_e32 v96, 1.0, v96
	v_rcp_f32_e32 v96, v96
	s_nop 0
	v_fmac_f32_e32 v164, v96, v154
	v_and_b32_e32 v96, 0xffff0000, v165
	v_add_f32_e32 v96, v241, v96
	v_mul_f32_e32 v96, 0xbfb8aa3b, v96
	v_exp_f32_e32 v96, v96
	v_and_b32_e32 v154, 0xffff0000, v161
	v_cndmask_b32_e64 v161, 0, v154, s[40:41]
	v_and_b32_e32 v154, 0xffff0000, v157
	v_add_f32_e32 v96, 1.0, v96
	v_rcp_f32_e32 v96, v96
; DI float bf2f(short b) { return __uint_as_float(((unsigned)(unsigned short)b) << 16); }
; DI bf16x8 pack8(const float* a) { u32x4 w = {cvtpk(a[0], a[1]), cvtpk(a[2], a[3]), cvtpk(a[4], a[5]), cvtpk(a[6], a[7])}; return *reinterpret_cast<bf16x8*>(&w); }
; DI float sigm(float x) { return __builtin_amdgcn_rcpf(1.f + __builtin_amdgcn_exp2f(-1.4426950408889634f * x)); }
; #define WAIT_L(n) asm volatile("s_waitcnt lgkmcnt(" #n ")":::"memory")
; #define BAR __builtin_amdgcn_s_barrier()
; #define WAIT_L(n) asm volatile("s_waitcnt lgkmcnt(" #n ")":::"memory")
; #define BAR __builtin_amdgcn_s_barrier()
; DI void gemm8_run(const GemmJob& ja, const GemmJob& jb, char* lds) {
;     ...
;           for (int it = 0; it < 4; ++it) { const int idx = (hb * 4 + it) * 512 + tid; const int r = idx >> 5, c16 = idx & 31; const size_t grow = (size_t)(brow + ai * 128 + r);
;             const float4 b0 = *reinterpret_cast<const float4*>(J.bias + bcol + c16 * 8), b1 = *reinterpret_cast<const float4*>(J.bias + bcol + c16 * 8 + 4);
;             const float bb[8] = {b0.x, b0.y, b0.z, b0.w, b1.x, b1.y, b1.z, b1.w};
;             float o8[8];
; #pragma unroll
;             for (int j = 0; j < 8; ++j) { const float g = sigm(bf2f(gv[it][j]) + bb[j]); o8[j] = (gb ? bf2f(ov[it][j]) : 0.f) + bf2f(av[it][j]) * g; }
;             *reinterpret_cast<bf16x8*>(J.C + grow * 1024 + bcol + c16 * 8) = pack8(o8); } }
;         WAIT_L(0); BAR;
	s_nop 0
	v_fmac_f32_e32 v161, v96, v154
	v_cvt_pk_bf16_f32 v154, v170, v158
	v_cvt_pk_bf16_f32 v155, v162, v159
	v_lshl_add_u64 v[158:159], v[182:183], 0, v[192:193]
	v_cvt_pk_bf16_f32 v156, v163, v160
	v_cvt_pk_bf16_f32 v157, v164, v161
	global_store_dwordx4 v[158:159], v[154:157], off
	s_nop 0
	v_lshlrev_b32_e32 v96, 16, v150
	v_lshlrev_b32_e32 v162, 16, v142
	v_and_b32_e32 v142, 0xffff0000, v142
	v_add_f32_e32 v96, v248, v96
	v_mul_f32_e32 v96, 0xbfb8aa3b, v96
	v_exp_f32_e32 v96, v96
	v_lshlrev_b32_e32 v158, 16, v146
	v_cndmask_b32_e64 v158, 0, v158, s[40:41]
	v_and_b32_e32 v146, 0xffff0000, v146
	v_add_f32_e32 v96, 1.0, v96
	v_rcp_f32_e32 v96, v96
	v_cndmask_b32_e64 v146, 0, v146, s[40:41]
	v_fmac_f32_e32 v158, v96, v162
	v_and_b32_e32 v96, 0xffff0000, v150
	v_add_f32_e32 v96, v249, v96
	v_mul_f32_e32 v96, 0xbfb8aa3b, v96
	v_exp_f32_e32 v96, v96
	s_nop 0
	v_add_f32_e32 v96, 1.0, v96
	v_rcp_f32_e32 v96, v96
	s_nop 0
	v_fmac_f32_e32 v146, v96, v142
	v_lshlrev_b32_e32 v96, 16, v151
	v_add_f32_e32 v96, v250, v96
	v_mul_f32_e32 v96, 0xbfb8aa3b, v96
	v_exp_f32_e32 v96, v96
	v_lshlrev_b32_e32 v142, 16, v147
	v_cndmask_b32_e64 v150, 0, v142, s[40:41]
	v_lshlrev_b32_e32 v142, 16, v143
	v_add_f32_e32 v96, 1.0, v96
	v_rcp_f32_e32 v96, v96
	s_nop 0
	v_fmac_f32_e32 v150, v96, v142
	v_and_b32_e32 v96, 0xffff0000, v151
	v_add_f32_e32 v96, v251, v96
	v_mul_f32_e32 v96, 0xbfb8aa3b, v96
	v_exp_f32_e32 v96, v96
	v_and_b32_e32 v142, 0xffff0000, v147
	v_cndmask_b32_e64 v147, 0, v142, s[40:41]
	v_and_b32_e32 v142, 0xffff0000, v143
	v_add_f32_e32 v96, 1.0, v96
	v_rcp_f32_e32 v96, v96
	s_nop 0
	v_fmac_f32_e32 v147, v96, v142
	v_lshlrev_b32_e32 v96, 16, v152
	v_add_f32_e32 v96, v238, v96
	v_mul_f32_e32 v96, 0xbfb8aa3b, v96
	v_exp_f32_e32 v96, v96
	v_lshlrev_b32_e32 v142, 16, v148
	v_cndmask_b32_e64 v151, 0, v142, s[40:41]
	v_lshlrev_b32_e32 v142, 16, v144
	v_add_f32_e32 v96, 1.0, v96
	v_rcp_f32_e32 v96, v96
	s_nop 0
	v_fmac_f32_e32 v151, v96, v142
	v_and_b32_e32 v96, 0xffff0000, v152
	v_add_f32_e32 v96, v239, v96
	v_mul_f32_e32 v96, 0xbfb8aa3b, v96
	v_exp_f32_e32 v96, v96
	v_and_b32_e32 v142, 0xffff0000, v148
	v_cndmask_b32_e64 v148, 0, v142, s[40:41]
	v_and_b32_e32 v142, 0xffff0000, v144
	v_add_f32_e32 v96, 1.0, v96
	v_rcp_f32_e32 v96, v96
	s_nop 0
	v_fmac_f32_e32 v148, v96, v142
	v_lshlrev_b32_e32 v96, 16, v153
	v_add_f32_e32 v96, v240, v96
	v_mul_f32_e32 v96, 0xbfb8aa3b, v96
	v_exp_f32_e32 v96, v96
	v_lshlrev_b32_e32 v142, 16, v149
	v_cndmask_b32_e64 v152, 0, v142, s[40:41]
	v_lshlrev_b32_e32 v142, 16, v145
	v_add_f32_e32 v96, 1.0, v96
	v_rcp_f32_e32 v96, v96
	s_nop 0
	v_fmac_f32_e32 v152, v96, v142
	v_and_b32_e32 v96, 0xffff0000, v153
	v_add_f32_e32 v96, v241, v96
	v_mul_f32_e32 v96, 0xbfb8aa3b, v96
	v_exp_f32_e32 v96, v96
	v_and_b32_e32 v142, 0xffff0000, v149
	v_cndmask_b32_e64 v149, 0, v142, s[40:41]
	v_and_b32_e32 v142, 0xffff0000, v145
	v_add_f32_e32 v96, 1.0, v96
	v_rcp_f32_e32 v96, v96
	s_nop 0
	v_fmac_f32_e32 v149, v96, v142
	v_cvt_pk_bf16_f32 v142, v158, v146
	v_cvt_pk_bf16_f32 v143, v150, v147
	v_lshl_add_u64 v[146:147], v[182:183], 0, v[190:191]
	v_cvt_pk_bf16_f32 v144, v151, v148
	v_cvt_pk_bf16_f32 v145, v152, v149
	global_store_dwordx4 v[146:147], v[142:145], off
	s_nop 0
	v_lshlrev_b32_e32 v96, 16, v138
	v_lshlrev_b32_e32 v150, 16, v130
	v_and_b32_e32 v130, 0xffff0000, v130
	v_add_f32_e32 v96, v248, v96
	v_mul_f32_e32 v96, 0xbfb8aa3b, v96
	v_exp_f32_e32 v96, v96
	v_lshlrev_b32_e32 v146, 16, v134
	v_cndmask_b32_e64 v146, 0, v146, s[40:41]
	v_and_b32_e32 v134, 0xffff0000, v134
	v_add_f32_e32 v96, 1.0, v96
	v_rcp_f32_e32 v96, v96
	v_cndmask_b32_e64 v134, 0, v134, s[40:41]
	v_fmac_f32_e32 v146, v96, v150
	v_and_b32_e32 v96, 0xffff0000, v138
	v_add_f32_e32 v96, v249, v96
	v_mul_f32_e32 v96, 0xbfb8aa3b, v96
	v_exp_f32_e32 v96, v96
	s_nop 0
	v_add_f32_e32 v96, 1.0, v96
	v_rcp_f32_e32 v96, v96
	s_nop 0
	v_fmac_f32_e32 v134, v96, v130
	v_lshlrev_b32_e32 v96, 16, v139
	v_add_f32_e32 v96, v250, v96
	v_mul_f32_e32 v96, 0xbfb8aa3b, v96
	v_exp_f32_e32 v96, v96
	v_lshlrev_b32_e32 v130, 16, v135
	v_cndmask_b32_e64 v138, 0, v130, s[40:41]
	v_lshlrev_b32_e32 v130, 16, v131
	v_add_f32_e32 v96, 1.0, v96
	v_rcp_f32_e32 v96, v96
	s_nop 0
	v_fmac_f32_e32 v138, v96, v130
	v_and_b32_e32 v96, 0xffff0000, v139
	v_add_f32_e32 v96, v251, v96
	v_mul_f32_e32 v96, 0xbfb8aa3b, v96
	v_exp_f32_e32 v96, v96
	v_and_b32_e32 v130, 0xffff0000, v135
	v_cndmask_b32_e64 v135, 0, v130, s[40:41]
	v_and_b32_e32 v130, 0xffff0000, v131
	v_add_f32_e32 v96, 1.0, v96
	v_rcp_f32_e32 v96, v96
	s_nop 0
	v_fmac_f32_e32 v135, v96, v130
	v_lshlrev_b32_e32 v96, 16, v140
	v_add_f32_e32 v96, v238, v96
	v_mul_f32_e32 v96, 0xbfb8aa3b, v96
	v_exp_f32_e32 v96, v96
	v_lshlrev_b32_e32 v130, 16, v136
	v_cndmask_b32_e64 v139, 0, v130, s[40:41]
	v_lshlrev_b32_e32 v130, 16, v132
	v_add_f32_e32 v96, 1.0, v96
	v_rcp_f32_e32 v96, v96
	s_nop 0
	v_fmac_f32_e32 v139, v96, v130
	v_and_b32_e32 v96, 0xffff0000, v140
	v_add_f32_e32 v96, v239, v96
	v_mul_f32_e32 v96, 0xbfb8aa3b, v96
	v_exp_f32_e32 v96, v96
	v_and_b32_e32 v130, 0xffff0000, v136
	v_cndmask_b32_e64 v136, 0, v130, s[40:41]
	v_and_b32_e32 v130, 0xffff0000, v132
	v_add_f32_e32 v96, 1.0, v96
	v_rcp_f32_e32 v96, v96
	s_nop 0
	v_fmac_f32_e32 v136, v96, v130
	v_lshlrev_b32_e32 v96, 16, v141
	v_add_f32_e32 v96, v240, v96
	v_mul_f32_e32 v96, 0xbfb8aa3b, v96
	v_exp_f32_e32 v96, v96
	v_lshlrev_b32_e32 v130, 16, v137
	v_cndmask_b32_e64 v140, 0, v130, s[40:41]
	v_lshlrev_b32_e32 v130, 16, v133
	v_add_f32_e32 v96, 1.0, v96
	v_rcp_f32_e32 v96, v96
	s_nop 0
	v_fmac_f32_e32 v140, v96, v130
	v_and_b32_e32 v96, 0xffff0000, v141
	v_add_f32_e32 v96, v241, v96
	v_mul_f32_e32 v96, 0xbfb8aa3b, v96
	v_exp_f32_e32 v96, v96
	v_and_b32_e32 v130, 0xffff0000, v137
	v_cndmask_b32_e64 v137, 0, v130, s[40:41]
	v_and_b32_e32 v130, 0xffff0000, v133
	v_add_f32_e32 v96, 1.0, v96
	v_rcp_f32_e32 v96, v96
	s_nop 0
	v_fmac_f32_e32 v137, v96, v130
	v_cvt_pk_bf16_f32 v130, v146, v134
	v_cvt_pk_bf16_f32 v131, v138, v135
	v_lshl_add_u64 v[134:135], v[182:183], 0, v[186:187]
	v_cvt_pk_bf16_f32 v132, v139, v136
	v_cvt_pk_bf16_f32 v133, v140, v137
	global_store_dwordx4 v[134:135], v[130:133], off
	s_waitcnt lgkmcnt(0)
	s_barrier
	s_branch .LBB0_191
